# scan: one s_waitcnt per step for all LDS operands instead of four
# speedup vs baseline: 1.0022x; 1.0022x over previous
; __device__ __forceinline__ void rwkv_scan2_item(const Params& p, int item, char* ldsraw) {
;     ...
;         R_LOAD(0)
;         float sakA = 0.f, sakB = 0.f;
; #pragma unroll
;         for (int q = 0; q < 16; q++) {
;           const f32x4 cw = nw, ckk = nkk, ckka = nkka, ck = nk; const float cvA = nvA, cvB = nvB;
;           if (q < 15) R_LOAD(q + 1)
;           __builtin_amdgcn_sched_barrier(0);
;           float mA0 = mul_s(a0, ckk.x), mA1 = mul_s(a2, ckk.z), mB0 = mul_s(b0, ckk.x), mB1 = mul_s(b2, ckk.z);
;           mA0 = fma_s(a1, ckk.y, mA0); mA1 = fma_s(a3, ckk.w, mA1); mB0 = fma_s(b1, ckk.y, mB0); mB1 = fma_s(b3, ckk.w, mB1);
;           float psA = add_s(mA0, mA1), psB = add_s(mB0, mB1);
;           psA = row16_sum(psA); psB = row16_sum(psB);
;           { const float t0 = fnma_s(psA, ckka.x, mul_s(cvA, ck.x)), t1 = fnma_s(psA, ckka.y, mul_s(cvA, ck.y));
;             const float t2 = fnma_s(psA, ckka.z, mul_s(cvA, ck.z)), t3 = fnma_s(psA, ckka.w, mul_s(cvA, ck.w));
;             a0 = fma_s(a0, cw.x, t0); a1 = fma_s(a1, cw.y, t1); a2 = fma_s(a2, cw.z, t2); a3 = fma_s(a3, cw.w, t3); }
;           { const float t0 = fnma_s(psB, ckka.x, mul_s(cvB, ck.x)), t1 = fnma_s(psB, ckka.y, mul_s(cvB, ck.y));
;             const float t2 = fnma_s(psB, ckka.z, mul_s(cvB, ck.z)), t3 = fnma_s(psB, ckka.w, mul_s(cvB, ck.w));
;             b0 = fma_s(b0, cw.x, t0); b1 = fma_s(b1, cw.y, t1); b2 = fma_s(b2, cw.z, t2); b3 = fma_s(b3, cw.w, t3); }
;           sakA = sel_eq(sakA, psA, jl, q); sakB = sel_eq(sakB, psB, jl, q);
;         }
;     ...
;         SA[(c & 1) * 256 + jl * 16 + row8] = sakA; SA[(c & 1) * 256 + jl * 16 + 8 + row8] = sakB;
;       }
;     } else {
;       if (c >= 1) {
;         const float* d = buf + bprev * CH + jl * 4;
;         const float* dvp = buf + bprev * CH + 320 + row8;
;         const float* dcp = buf + bprev * CH + 336;
;         const float* sap = SA + ((c - 1) & 1) * 256 + row8;
;         f32x4 nw, nkka, nk, nwr; float nvA, nvB, nsA, nsB; f32x2 ncc;
;     ...
;         Y_LOAD(0)
;         float ykA = 0.f, ykB = 0.f;
; #pragma unroll
;         for (int q = 0; q < 16; q++) {
;           const f32x4 cw = nw, ckka = nkka, ck = nk, cwr = nwr; const float cvA = nvA, cvB = nvB, psA = nsA, psB = nsB; const f32x2 ccc = ncc;
;           if (q < 15) Y_LOAD(q + 1)
;           __builtin_amdgcn_sched_barrier(0);
.Lsc_loop:
	global_load_dwordx4 v[20:23], v12, s[24:25]
	global_load_dwordx2 v[24:25], v13, s[26:27]
	global_load_dwordx2 v[26:27], v13, s[26:27] offset:128
	global_load_dwordx2 v[28:29], v13, s[26:27] offset:256
	global_load_dwordx2 v[30:31], v13, s[26:27] offset:384
	global_load_ushort v32, v14, s[26:27]
	global_load_dwordx2 v[34:35], v15, s[28:29]
	ds_read_b128 v[44:47], v0 offset:256
	ds_read_b128 v[48:51], v0 offset:512
	ds_read_b128 v[56:59], v0 offset:1024
	ds_read_b128 v[40:43], v0 offset:0
	ds_read_b128 v[52:55], v0 offset:768
	ds_read_b128 v[80:83], v1 offset:0
	ds_read_b128 v[64:67], v0 offset:1536
	ds_read_b128 v[68:71], v0 offset:1792
	ds_read_b128 v[76:79], v0 offset:2304
	ds_read_b128 v[60:63], v0 offset:1280
	ds_read_b128 v[72:75], v0 offset:2048
	s_waitcnt lgkmcnt(5)
	v_pk_mul_f32 v[88:89], v[4:5], v[44:45] op_sel_hi:[0,1]
	v_pk_mul_f32 v[90:91], v[6:7], v[48:49] op_sel_hi:[0,1]
	v_pk_fma_f32 v[88:89], v[4:5], v[46:47], v[88:89] op_sel:[1,0,0] op_sel_hi:[1,1,1]
	v_pk_fma_f32 v[90:91], v[6:7], v[50:51], v[90:91] op_sel:[1,0,0] op_sel_hi:[1,1,1]
	v_pk_add_f32 v[100:101], v[88:89], v[90:91]
	v_pk_mul_f32 v[96:97], v[80:81], v[56:57] op_sel:[0,0] op_sel_hi:[0,1]
	v_pk_mul_f32 v[98:99], v[80:81], v[58:59] op_sel:[0,0] op_sel_hi:[0,1]
	v_add_f32_dpp v93, v100, v100 quad_perm:[1,0,3,2] row_mask:0xf bank_mask:0xf
	v_pk_fma_f32 v[96:97], v[4:5], v[40:41], v[96:97]
	v_pk_fma_f32 v[98:99], v[6:7], v[42:43], v[98:99]
	v_add_f32_dpp v92, v93, v93 quad_perm:[2,3,0,1] row_mask:0xf bank_mask:0xf
	ds_read_b128 v[142:145], v0 offset:2816
	ds_read_b128 v[146:149], v0 offset:3072
	v_add_f32_dpp v93, v92, v92 row_ror:4 row_mask:0xf bank_mask:0xf
	ds_read_b128 v[154:157], v0 offset:3584
	ds_read_b128 v[138:141], v0 offset:2560
	v_add_f32_dpp v94, v93, v93 row_ror:8 row_mask:0xf bank_mask:0xf
	v_add_f32_dpp v108, v93, v93 row_ror:8 row_mask:0xf bank_mask:0x1
	ds_read_b128 v[150:153], v0 offset:3328
	v_pk_fma_f32 v[4:5], v[94:95], v[52:53], v[96:97] op_sel_hi:[0,1,1] neg_lo:[1,0,0] neg_hi:[1,0,0]
	v_pk_fma_f32 v[6:7], v[94:95], v[54:55], v[98:99] op_sel_hi:[0,1,1] neg_lo:[1,0,0] neg_hi:[1,0,0]
	s_waitcnt lgkmcnt(5)
	v_pk_mul_f32 v[88:89], v[4:5], v[64:65] op_sel_hi:[0,1]
	v_pk_mul_f32 v[90:91], v[6:7], v[68:69] op_sel_hi:[0,1]
	v_pk_fma_f32 v[88:89], v[4:5], v[66:67], v[88:89] op_sel:[1,0,0] op_sel_hi:[1,1,1]
	v_pk_fma_f32 v[90:91], v[6:7], v[70:71], v[90:91] op_sel:[1,0,0] op_sel_hi:[1,1,1]
	v_pk_add_f32 v[102:103], v[88:89], v[90:91]
	v_pk_mul_f32 v[96:97], v[80:81], v[76:77] op_sel:[1,0] op_sel_hi:[1,1]
	v_pk_mul_f32 v[98:99], v[80:81], v[78:79] op_sel:[1,0] op_sel_hi:[1,1]
	v_add_f32_dpp v93, v102, v102 quad_perm:[1,0,3,2] row_mask:0xf bank_mask:0xf
	v_pk_fma_f32 v[96:97], v[4:5], v[60:61], v[96:97]
	v_pk_fma_f32 v[98:99], v[6:7], v[62:63], v[98:99]
	v_add_f32_dpp v92, v93, v93 quad_perm:[2,3,0,1] row_mask:0xf bank_mask:0xf
	ds_read_b128 v[44:47], v0 offset:4096
	ds_read_b128 v[48:51], v0 offset:4352
	v_add_f32_dpp v93, v92, v92 row_ror:4 row_mask:0xf bank_mask:0xf
	ds_read_b128 v[56:59], v0 offset:4864
	ds_read_b128 v[40:43], v0 offset:3840
	v_add_f32_dpp v94, v93, v93 row_ror:8 row_mask:0xf bank_mask:0xf
	v_add_f32_dpp v108, v93, v93 row_ror:8 row_mask:0xf bank_mask:0x4
	ds_read_b128 v[52:55], v0 offset:4608
	v_pk_fma_f32 v[4:5], v[94:95], v[72:73], v[96:97] op_sel_hi:[0,1,1] neg_lo:[1,0,0] neg_hi:[1,0,0]
	v_pk_fma_f32 v[6:7], v[94:95], v[74:75], v[98:99] op_sel_hi:[0,1,1] neg_lo:[1,0,0] neg_hi:[1,0,0]
	ds_read_b128 v[84:87], v1 offset:16
	v_add_f32_dpp v101, v101, v101 row_ror:8 row_mask:0xf bank_mask:0x3
	s_nop 1
	v_add_f32_dpp v101, v103, v103 row_ror:8 row_mask:0xf bank_mask:0xc
	s_waitcnt lgkmcnt(6)
	v_pk_mul_f32 v[88:89], v[4:5], v[142:143] op_sel_hi:[0,1]
	v_pk_mul_f32 v[90:91], v[6:7], v[146:147] op_sel_hi:[0,1]
	v_pk_fma_f32 v[88:89], v[4:5], v[144:145], v[88:89] op_sel:[1,0,0] op_sel_hi:[1,1,1]
	v_pk_fma_f32 v[90:91], v[6:7], v[148:149], v[90:91] op_sel:[1,0,0] op_sel_hi:[1,1,1]
	v_pk_add_f32 v[104:105], v[88:89], v[90:91]
	v_pk_mul_f32 v[96:97], v[82:83], v[154:155] op_sel:[0,0] op_sel_hi:[0,1]
	v_pk_mul_f32 v[98:99], v[82:83], v[156:157] op_sel:[0,0] op_sel_hi:[0,1]
	v_add_f32_dpp v93, v104, v104 quad_perm:[1,0,3,2] row_mask:0xf bank_mask:0xf
	v_pk_fma_f32 v[96:97], v[4:5], v[138:139], v[96:97]
	v_pk_fma_f32 v[98:99], v[6:7], v[140:141], v[98:99]
	v_add_f32_dpp v92, v93, v93 quad_perm:[2,3,0,1] row_mask:0xf bank_mask:0xf
	ds_read_b128 v[64:67], v0 offset:5376
	ds_read_b128 v[68:71], v0 offset:5632
	v_add_f32_dpp v93, v92, v92 row_ror:4 row_mask:0xf bank_mask:0xf
	ds_read_b128 v[76:79], v0 offset:6144
	ds_read_b128 v[60:63], v0 offset:5120
	v_add_f32_dpp v94, v93, v93 row_ror:8 row_mask:0xf bank_mask:0xf
	v_add_f32_dpp v108, v93, v93 row_ror:8 row_mask:0xf bank_mask:0x2
	ds_read_b128 v[72:75], v0 offset:5888
	v_pk_fma_f32 v[4:5], v[94:95], v[150:151], v[96:97] op_sel_hi:[0,1,1] neg_lo:[1,0,0] neg_hi:[1,0,0]
	v_pk_fma_f32 v[6:7], v[94:95], v[152:153], v[98:99] op_sel_hi:[0,1,1] neg_lo:[1,0,0] neg_hi:[1,0,0]
	s_waitcnt lgkmcnt(6)
; __device__ __forceinline__ void rwkv_scan2_item(const Params& p, int item, char* ldsraw) {
;     ...
;         R_LOAD(0)
;         float sakA = 0.f, sakB = 0.f;
; #pragma unroll
;         for (int q = 0; q < 16; q++) {
;           const f32x4 cw = nw, ckk = nkk, ckka = nkka, ck = nk; const float cvA = nvA, cvB = nvB;
;           if (q < 15) R_LOAD(q + 1)
;           __builtin_amdgcn_sched_barrier(0);
;           float mA0 = mul_s(a0, ckk.x), mA1 = mul_s(a2, ckk.z), mB0 = mul_s(b0, ckk.x), mB1 = mul_s(b2, ckk.z);
;           mA0 = fma_s(a1, ckk.y, mA0); mA1 = fma_s(a3, ckk.w, mA1); mB0 = fma_s(b1, ckk.y, mB0); mB1 = fma_s(b3, ckk.w, mB1);
;           float psA = add_s(mA0, mA1), psB = add_s(mB0, mB1);
;           psA = row16_sum(psA); psB = row16_sum(psB);
;           { const float t0 = fnma_s(psA, ckka.x, mul_s(cvA, ck.x)), t1 = fnma_s(psA, ckka.y, mul_s(cvA, ck.y));
;             const float t2 = fnma_s(psA, ckka.z, mul_s(cvA, ck.z)), t3 = fnma_s(psA, ckka.w, mul_s(cvA, ck.w));
;             a0 = fma_s(a0, cw.x, t0); a1 = fma_s(a1, cw.y, t1); a2 = fma_s(a2, cw.z, t2); a3 = fma_s(a3, cw.w, t3); }
;           { const float t0 = fnma_s(psB, ckka.x, mul_s(cvB, ck.x)), t1 = fnma_s(psB, ckka.y, mul_s(cvB, ck.y));
;             const float t2 = fnma_s(psB, ckka.z, mul_s(cvB, ck.z)), t3 = fnma_s(psB, ckka.w, mul_s(cvB, ck.w));
;             b0 = fma_s(b0, cw.x, t0); b1 = fma_s(b1, cw.y, t1); b2 = fma_s(b2, cw.z, t2); b3 = fma_s(b3, cw.w, t3); }
;           sakA = sel_eq(sakA, psA, jl, q); sakB = sel_eq(sakB, psB, jl, q);
;         }
;     ...
;         SA[(c & 1) * 256 + jl * 16 + row8] = sakA; SA[(c & 1) * 256 + jl * 16 + 8 + row8] = sakB;
;       }
;     } else {
;       if (c >= 1) {
;         const float* d = buf + bprev * CH + jl * 4;
;         const float* dvp = buf + bprev * CH + 320 + row8;
;         const float* dcp = buf + bprev * CH + 336;
;         const float* sap = SA + ((c - 1) & 1) * 256 + row8;
;         f32x4 nw, nkka, nk, nwr; float nvA, nvB, nsA, nsB; f32x2 ncc;
;     ...
;         Y_LOAD(0)
;         float ykA = 0.f, ykB = 0.f;
; #pragma unroll
;         for (int q = 0; q < 16; q++) {
;           const f32x4 cw = nw, ckka = nkka, ck = nk, cwr = nwr; const float cvA = nvA, cvB = nvB, psA = nsA, psB = nsB; const f32x2 ccc = ncc;
;           if (q < 15) Y_LOAD(q + 1)
;           __builtin_amdgcn_sched_barrier(0);
	v_pk_mul_f32 v[88:89], v[4:5], v[44:45] op_sel_hi:[0,1]
	v_pk_mul_f32 v[90:91], v[6:7], v[48:49] op_sel_hi:[0,1]
	v_pk_fma_f32 v[88:89], v[4:5], v[46:47], v[88:89] op_sel:[1,0,0] op_sel_hi:[1,1,1]
	v_pk_fma_f32 v[90:91], v[6:7], v[50:51], v[90:91] op_sel:[1,0,0] op_sel_hi:[1,1,1]
	v_pk_add_f32 v[132:133], v[88:89], v[90:91]
	v_pk_mul_f32 v[96:97], v[82:83], v[56:57] op_sel:[1,0] op_sel_hi:[1,1]
	v_pk_mul_f32 v[98:99], v[82:83], v[58:59] op_sel:[1,0] op_sel_hi:[1,1]
	v_add_f32_dpp v93, v132, v132 quad_perm:[1,0,3,2] row_mask:0xf bank_mask:0xf
	v_pk_fma_f32 v[96:97], v[4:5], v[40:41], v[96:97]
	v_pk_fma_f32 v[98:99], v[6:7], v[42:43], v[98:99]
	v_add_f32_dpp v92, v93, v93 quad_perm:[2,3,0,1] row_mask:0xf bank_mask:0xf
	ds_read_b128 v[142:145], v0 offset:6656
	ds_read_b128 v[146:149], v0 offset:6912
	v_add_f32_dpp v93, v92, v92 row_ror:4 row_mask:0xf bank_mask:0xf
	ds_read_b128 v[154:157], v0 offset:7424
	ds_read_b128 v[138:141], v0 offset:6400
	v_add_f32_dpp v94, v93, v93 row_ror:8 row_mask:0xf bank_mask:0xf
	v_add_f32_dpp v108, v93, v93 row_ror:8 row_mask:0xf bank_mask:0x8
	ds_read_b128 v[150:153], v0 offset:7168
	v_pk_fma_f32 v[4:5], v[94:95], v[52:53], v[96:97] op_sel_hi:[0,1,1] neg_lo:[1,0,0] neg_hi:[1,0,0]
	v_pk_fma_f32 v[6:7], v[94:95], v[54:55], v[98:99] op_sel_hi:[0,1,1] neg_lo:[1,0,0] neg_hi:[1,0,0]
	v_add_f32_dpp v105, v105, v105 row_ror:8 row_mask:0xf bank_mask:0x3
	s_nop 1
	v_add_f32_dpp v105, v133, v133 row_ror:8 row_mask:0xf bank_mask:0xc
	v_add_f32_dpp v101, v101, v101 row_half_mirror row_mask:0xf bank_mask:0x5
	s_nop 1
	v_add_f32_dpp v101, v105, v105 row_half_mirror row_mask:0xf bank_mask:0xa
	s_waitcnt lgkmcnt(5)
	v_pk_mul_f32 v[88:89], v[4:5], v[64:65] op_sel_hi:[0,1]
	v_pk_mul_f32 v[90:91], v[6:7], v[68:69] op_sel_hi:[0,1]
	v_pk_fma_f32 v[88:89], v[4:5], v[66:67], v[88:89] op_sel:[1,0,0] op_sel_hi:[1,1,1]
	v_pk_fma_f32 v[90:91], v[6:7], v[70:71], v[90:91] op_sel:[1,0,0] op_sel_hi:[1,1,1]
	v_pk_add_f32 v[134:135], v[88:89], v[90:91]
	v_pk_mul_f32 v[96:97], v[84:85], v[76:77] op_sel:[0,0] op_sel_hi:[0,1]
	v_pk_mul_f32 v[98:99], v[84:85], v[78:79] op_sel:[0,0] op_sel_hi:[0,1]
	v_add_f32_dpp v93, v134, v134 quad_perm:[1,0,3,2] row_mask:0xf bank_mask:0xf
	v_pk_fma_f32 v[96:97], v[4:5], v[60:61], v[96:97]
	v_pk_fma_f32 v[98:99], v[6:7], v[62:63], v[98:99]
	v_add_f32_dpp v92, v93, v93 quad_perm:[2,3,0,1] row_mask:0xf bank_mask:0xf
	ds_read_b128 v[44:47], v0 offset:7936
	ds_read_b128 v[48:51], v0 offset:8192
	v_add_f32_dpp v93, v92, v92 row_ror:4 row_mask:0xf bank_mask:0xf
	ds_read_b128 v[56:59], v0 offset:8704
	ds_read_b128 v[40:43], v0 offset:7680
	v_add_f32_dpp v94, v93, v93 row_ror:8 row_mask:0xf bank_mask:0xf
	v_add_f32_dpp v109, v93, v93 row_ror:8 row_mask:0xf bank_mask:0x1
	ds_read_b128 v[52:55], v0 offset:8448
	v_pk_fma_f32 v[4:5], v[94:95], v[72:73], v[96:97] op_sel_hi:[0,1,1] neg_lo:[1,0,0] neg_hi:[1,0,0]
	v_pk_fma_f32 v[6:7], v[94:95], v[74:75], v[98:99] op_sel_hi:[0,1,1] neg_lo:[1,0,0] neg_hi:[1,0,0]
	s_waitcnt lgkmcnt(5)
	v_pk_mul_f32 v[88:89], v[4:5], v[142:143] op_sel_hi:[0,1]
	v_pk_mul_f32 v[90:91], v[6:7], v[146:147] op_sel_hi:[0,1]
	v_pk_fma_f32 v[88:89], v[4:5], v[144:145], v[88:89] op_sel:[1,0,0] op_sel_hi:[1,1,1]
	v_pk_fma_f32 v[90:91], v[6:7], v[148:149], v[90:91] op_sel:[1,0,0] op_sel_hi:[1,1,1]
	v_pk_add_f32 v[136:137], v[88:89], v[90:91]
	v_pk_mul_f32 v[96:97], v[84:85], v[154:155] op_sel:[1,0] op_sel_hi:[1,1]
	v_pk_mul_f32 v[98:99], v[84:85], v[156:157] op_sel:[1,0] op_sel_hi:[1,1]
	v_add_f32_dpp v93, v136, v136 quad_perm:[1,0,3,2] row_mask:0xf bank_mask:0xf
	v_pk_fma_f32 v[96:97], v[4:5], v[138:139], v[96:97]
	v_pk_fma_f32 v[98:99], v[6:7], v[140:141], v[98:99]
	v_add_f32_dpp v92, v93, v93 quad_perm:[2,3,0,1] row_mask:0xf bank_mask:0xf
	ds_read_b128 v[64:67], v0 offset:9216
	ds_read_b128 v[68:71], v0 offset:9472
	v_add_f32_dpp v93, v92, v92 row_ror:4 row_mask:0xf bank_mask:0xf
	ds_read_b128 v[76:79], v0 offset:9984
	ds_read_b128 v[60:63], v0 offset:8960
	v_add_f32_dpp v94, v93, v93 row_ror:8 row_mask:0xf bank_mask:0xf
	v_add_f32_dpp v109, v93, v93 row_ror:8 row_mask:0xf bank_mask:0x4
	ds_read_b128 v[72:75], v0 offset:9728
	v_pk_fma_f32 v[4:5], v[94:95], v[150:151], v[96:97] op_sel_hi:[0,1,1] neg_lo:[1,0,0] neg_hi:[1,0,0]
	v_pk_fma_f32 v[6:7], v[94:95], v[152:153], v[98:99] op_sel_hi:[0,1,1] neg_lo:[1,0,0] neg_hi:[1,0,0]
	ds_read_b128 v[80:83], v1 offset:32
	v_add_f32_dpp v135, v135, v135 row_ror:8 row_mask:0xf bank_mask:0x3
	s_nop 1
	v_add_f32_dpp v135, v137, v137 row_ror:8 row_mask:0xf bank_mask:0xc
	s_waitcnt lgkmcnt(6)
	v_pk_mul_f32 v[88:89], v[4:5], v[44:45] op_sel_hi:[0,1]
	v_pk_mul_f32 v[90:91], v[6:7], v[48:49] op_sel_hi:[0,1]
	v_pk_fma_f32 v[88:89], v[4:5], v[46:47], v[88:89] op_sel:[1,0,0] op_sel_hi:[1,1,1]
	v_pk_fma_f32 v[90:91], v[6:7], v[50:51], v[90:91] op_sel:[1,0,0] op_sel_hi:[1,1,1]
	v_pk_add_f32 v[102:103], v[88:89], v[90:91]
	v_pk_mul_f32 v[96:97], v[86:87], v[56:57] op_sel:[0,0] op_sel_hi:[0,1]
	v_pk_mul_f32 v[98:99], v[86:87], v[58:59] op_sel:[0,0] op_sel_hi:[0,1]
	v_add_f32_dpp v93, v102, v102 quad_perm:[1,0,3,2] row_mask:0xf bank_mask:0xf
	v_pk_fma_f32 v[96:97], v[4:5], v[40:41], v[96:97]
	v_pk_fma_f32 v[98:99], v[6:7], v[42:43], v[98:99]
	v_add_f32_dpp v92, v93, v93 quad_perm:[2,3,0,1] row_mask:0xf bank_mask:0xf
	ds_read_b128 v[142:145], v0 offset:10496
	ds_read_b128 v[146:149], v0 offset:10752
	v_add_f32_dpp v93, v92, v92 row_ror:4 row_mask:0xf bank_mask:0xf
	ds_read_b128 v[154:157], v0 offset:11264
	ds_read_b128 v[138:141], v0 offset:10240
	v_add_f32_dpp v94, v93, v93 row_ror:8 row_mask:0xf bank_mask:0xf
	v_add_f32_dpp v109, v93, v93 row_ror:8 row_mask:0xf bank_mask:0x2
	ds_read_b128 v[150:153], v0 offset:11008
	v_pk_fma_f32 v[4:5], v[94:95], v[52:53], v[96:97] op_sel_hi:[0,1,1] neg_lo:[1,0,0] neg_hi:[1,0,0]
	v_pk_fma_f32 v[6:7], v[94:95], v[54:55], v[98:99] op_sel_hi:[0,1,1] neg_lo:[1,0,0] neg_hi:[1,0,0]
	s_waitcnt lgkmcnt(6)
; __device__ __forceinline__ void rwkv_scan2_item(const Params& p, int item, char* ldsraw) {
;     ...
;         R_LOAD(0)
;         float sakA = 0.f, sakB = 0.f;
; #pragma unroll
;         for (int q = 0; q < 16; q++) {
;           const f32x4 cw = nw, ckk = nkk, ckka = nkka, ck = nk; const float cvA = nvA, cvB = nvB;
;           if (q < 15) R_LOAD(q + 1)
;           __builtin_amdgcn_sched_barrier(0);
;           float mA0 = mul_s(a0, ckk.x), mA1 = mul_s(a2, ckk.z), mB0 = mul_s(b0, ckk.x), mB1 = mul_s(b2, ckk.z);
;           mA0 = fma_s(a1, ckk.y, mA0); mA1 = fma_s(a3, ckk.w, mA1); mB0 = fma_s(b1, ckk.y, mB0); mB1 = fma_s(b3, ckk.w, mB1);
;           float psA = add_s(mA0, mA1), psB = add_s(mB0, mB1);
;           psA = row16_sum(psA); psB = row16_sum(psB);
;           { const float t0 = fnma_s(psA, ckka.x, mul_s(cvA, ck.x)), t1 = fnma_s(psA, ckka.y, mul_s(cvA, ck.y));
;             const float t2 = fnma_s(psA, ckka.z, mul_s(cvA, ck.z)), t3 = fnma_s(psA, ckka.w, mul_s(cvA, ck.w));
;             a0 = fma_s(a0, cw.x, t0); a1 = fma_s(a1, cw.y, t1); a2 = fma_s(a2, cw.z, t2); a3 = fma_s(a3, cw.w, t3); }
;           { const float t0 = fnma_s(psB, ckka.x, mul_s(cvB, ck.x)), t1 = fnma_s(psB, ckka.y, mul_s(cvB, ck.y));
;             const float t2 = fnma_s(psB, ckka.z, mul_s(cvB, ck.z)), t3 = fnma_s(psB, ckka.w, mul_s(cvB, ck.w));
;             b0 = fma_s(b0, cw.x, t0); b1 = fma_s(b1, cw.y, t1); b2 = fma_s(b2, cw.z, t2); b3 = fma_s(b3, cw.w, t3); }
;           sakA = sel_eq(sakA, psA, jl, q); sakB = sel_eq(sakB, psB, jl, q);
;         }
;     ...
;         SA[(c & 1) * 256 + jl * 16 + row8] = sakA; SA[(c & 1) * 256 + jl * 16 + 8 + row8] = sakB;
;       }
;     } else {
;       if (c >= 1) {
;         const float* d = buf + bprev * CH + jl * 4;
;         const float* dvp = buf + bprev * CH + 320 + row8;
;         const float* dcp = buf + bprev * CH + 336;
;         const float* sap = SA + ((c - 1) & 1) * 256 + row8;
;         f32x4 nw, nkka, nk, nwr; float nvA, nvB, nsA, nsB; f32x2 ncc;
;     ...
;         Y_LOAD(0)
;         float ykA = 0.f, ykB = 0.f;
; #pragma unroll
;         for (int q = 0; q < 16; q++) {
;           const f32x4 cw = nw, ckka = nkka, ck = nk, cwr = nwr; const float cvA = nvA, cvB = nvB, psA = nsA, psB = nsB; const f32x2 ccc = ncc;
;           if (q < 15) Y_LOAD(q + 1)
;           __builtin_amdgcn_sched_barrier(0);
	v_pk_mul_f32 v[88:89], v[4:5], v[64:65] op_sel_hi:[0,1]
	v_pk_mul_f32 v[90:91], v[6:7], v[68:69] op_sel_hi:[0,1]
	v_pk_fma_f32 v[88:89], v[4:5], v[66:67], v[88:89] op_sel:[1,0,0] op_sel_hi:[1,1,1]
	v_pk_fma_f32 v[90:91], v[6:7], v[70:71], v[90:91] op_sel:[1,0,0] op_sel_hi:[1,1,1]
	v_pk_add_f32 v[132:133], v[88:89], v[90:91]
	v_pk_mul_f32 v[96:97], v[86:87], v[76:77] op_sel:[1,0] op_sel_hi:[1,1]
	v_pk_mul_f32 v[98:99], v[86:87], v[78:79] op_sel:[1,0] op_sel_hi:[1,1]
	v_add_f32_dpp v93, v132, v132 quad_perm:[1,0,3,2] row_mask:0xf bank_mask:0xf
	v_pk_fma_f32 v[96:97], v[4:5], v[60:61], v[96:97]
	v_pk_fma_f32 v[98:99], v[6:7], v[62:63], v[98:99]
	v_add_f32_dpp v92, v93, v93 quad_perm:[2,3,0,1] row_mask:0xf bank_mask:0xf
	ds_read_b128 v[44:47], v0 offset:11776
	ds_read_b128 v[48:51], v0 offset:12032
	v_add_f32_dpp v93, v92, v92 row_ror:4 row_mask:0xf bank_mask:0xf
	ds_read_b128 v[56:59], v0 offset:12544
	ds_read_b128 v[40:43], v0 offset:11520
	v_add_f32_dpp v94, v93, v93 row_ror:8 row_mask:0xf bank_mask:0xf
	v_add_f32_dpp v109, v93, v93 row_ror:8 row_mask:0xf bank_mask:0x8
	ds_read_b128 v[52:55], v0 offset:12288
	v_pk_fma_f32 v[4:5], v[94:95], v[72:73], v[96:97] op_sel_hi:[0,1,1] neg_lo:[1,0,0] neg_hi:[1,0,0]
	v_pk_fma_f32 v[6:7], v[94:95], v[74:75], v[98:99] op_sel_hi:[0,1,1] neg_lo:[1,0,0] neg_hi:[1,0,0]
	v_add_f32_dpp v103, v103, v103 row_ror:8 row_mask:0xf bank_mask:0x3
	s_nop 1
	v_add_f32_dpp v103, v133, v133 row_ror:8 row_mask:0xf bank_mask:0xc
	v_add_f32_dpp v135, v135, v135 row_half_mirror row_mask:0xf bank_mask:0x5
	s_nop 1
	v_add_f32_dpp v135, v103, v103 row_half_mirror row_mask:0xf bank_mask:0xa
	v_cndmask_b32_e64 v106, v135, v101, s[36:37]
	v_cndmask_b32_e64 v107, v101, v135, s[36:37]
	s_nop 1
	v_add_f32_dpp v101, v106, v107 quad_perm:[2,3,0,1] row_mask:0xf bank_mask:0xf
	s_waitcnt lgkmcnt(5)
	v_pk_mul_f32 v[88:89], v[4:5], v[142:143] op_sel_hi:[0,1]
	v_pk_mul_f32 v[90:91], v[6:7], v[146:147] op_sel_hi:[0,1]
	v_pk_fma_f32 v[88:89], v[4:5], v[144:145], v[88:89] op_sel:[1,0,0] op_sel_hi:[1,1,1]
	v_pk_fma_f32 v[90:91], v[6:7], v[148:149], v[90:91] op_sel:[1,0,0] op_sel_hi:[1,1,1]
	v_pk_add_f32 v[104:105], v[88:89], v[90:91]
	v_pk_mul_f32 v[96:97], v[80:81], v[154:155] op_sel:[0,0] op_sel_hi:[0,1]
	v_pk_mul_f32 v[98:99], v[80:81], v[156:157] op_sel:[0,0] op_sel_hi:[0,1]
	v_add_f32_dpp v93, v104, v104 quad_perm:[1,0,3,2] row_mask:0xf bank_mask:0xf
	v_pk_fma_f32 v[96:97], v[4:5], v[138:139], v[96:97]
	v_pk_fma_f32 v[98:99], v[6:7], v[140:141], v[98:99]
	v_add_f32_dpp v92, v93, v93 quad_perm:[2,3,0,1] row_mask:0xf bank_mask:0xf
	ds_read_b128 v[64:67], v0 offset:13056
	ds_read_b128 v[68:71], v0 offset:13312
	v_add_f32_dpp v93, v92, v92 row_ror:4 row_mask:0xf bank_mask:0xf
	ds_read_b128 v[76:79], v0 offset:13824
	ds_read_b128 v[60:63], v0 offset:12800
	v_add_f32_dpp v94, v93, v93 row_ror:8 row_mask:0xf bank_mask:0xf
	v_add_f32_dpp v110, v93, v93 row_ror:8 row_mask:0xf bank_mask:0x1
	ds_read_b128 v[72:75], v0 offset:13568
	v_pk_fma_f32 v[4:5], v[94:95], v[150:151], v[96:97] op_sel_hi:[0,1,1] neg_lo:[1,0,0] neg_hi:[1,0,0]
	v_pk_fma_f32 v[6:7], v[94:95], v[152:153], v[98:99] op_sel_hi:[0,1,1] neg_lo:[1,0,0] neg_hi:[1,0,0]
	s_waitcnt lgkmcnt(5)
	v_pk_mul_f32 v[88:89], v[4:5], v[44:45] op_sel_hi:[0,1]
	v_pk_mul_f32 v[90:91], v[6:7], v[48:49] op_sel_hi:[0,1]
	v_pk_fma_f32 v[88:89], v[4:5], v[46:47], v[88:89] op_sel:[1,0,0] op_sel_hi:[1,1,1]
	v_pk_fma_f32 v[90:91], v[6:7], v[50:51], v[90:91] op_sel:[1,0,0] op_sel_hi:[1,1,1]
	v_pk_add_f32 v[136:137], v[88:89], v[90:91]
	v_pk_mul_f32 v[96:97], v[80:81], v[56:57] op_sel:[1,0] op_sel_hi:[1,1]
	v_pk_mul_f32 v[98:99], v[80:81], v[58:59] op_sel:[1,0] op_sel_hi:[1,1]
	v_add_f32_dpp v93, v136, v136 quad_perm:[1,0,3,2] row_mask:0xf bank_mask:0xf
	v_pk_fma_f32 v[96:97], v[4:5], v[40:41], v[96:97]
	v_pk_fma_f32 v[98:99], v[6:7], v[42:43], v[98:99]
	v_add_f32_dpp v92, v93, v93 quad_perm:[2,3,0,1] row_mask:0xf bank_mask:0xf
	ds_read_b128 v[142:145], v0 offset:14336
	ds_read_b128 v[146:149], v0 offset:14592
	v_add_f32_dpp v93, v92, v92 row_ror:4 row_mask:0xf bank_mask:0xf
	ds_read_b128 v[154:157], v0 offset:15104
	ds_read_b128 v[138:141], v0 offset:14080
	v_add_f32_dpp v94, v93, v93 row_ror:8 row_mask:0xf bank_mask:0xf
	v_add_f32_dpp v110, v93, v93 row_ror:8 row_mask:0xf bank_mask:0x4
	ds_read_b128 v[150:153], v0 offset:14848
	v_pk_fma_f32 v[4:5], v[94:95], v[52:53], v[96:97] op_sel_hi:[0,1,1] neg_lo:[1,0,0] neg_hi:[1,0,0]
	v_pk_fma_f32 v[6:7], v[94:95], v[54:55], v[98:99] op_sel_hi:[0,1,1] neg_lo:[1,0,0] neg_hi:[1,0,0]
	ds_read_b128 v[84:87], v1 offset:48
	v_add_f32_dpp v105, v105, v105 row_ror:8 row_mask:0xf bank_mask:0x3
	s_nop 1
	v_add_f32_dpp v105, v137, v137 row_ror:8 row_mask:0xf bank_mask:0xc
	s_waitcnt lgkmcnt(6)
	v_pk_mul_f32 v[88:89], v[4:5], v[64:65] op_sel_hi:[0,1]
	v_pk_mul_f32 v[90:91], v[6:7], v[68:69] op_sel_hi:[0,1]
	v_pk_fma_f32 v[88:89], v[4:5], v[66:67], v[88:89] op_sel:[1,0,0] op_sel_hi:[1,1,1]
	v_pk_fma_f32 v[90:91], v[6:7], v[70:71], v[90:91] op_sel:[1,0,0] op_sel_hi:[1,1,1]
	v_pk_add_f32 v[132:133], v[88:89], v[90:91]
	v_pk_mul_f32 v[96:97], v[82:83], v[76:77] op_sel:[0,0] op_sel_hi:[0,1]
	v_pk_mul_f32 v[98:99], v[82:83], v[78:79] op_sel:[0,0] op_sel_hi:[0,1]
	v_add_f32_dpp v93, v132, v132 quad_perm:[1,0,3,2] row_mask:0xf bank_mask:0xf
	v_pk_fma_f32 v[96:97], v[4:5], v[60:61], v[96:97]
	v_pk_fma_f32 v[98:99], v[6:7], v[62:63], v[98:99]
	v_add_f32_dpp v92, v93, v93 quad_perm:[2,3,0,1] row_mask:0xf bank_mask:0xf
	ds_read_b128 v[44:47], v0 offset:15616
	ds_read_b128 v[48:51], v0 offset:15872
	v_add_f32_dpp v93, v92, v92 row_ror:4 row_mask:0xf bank_mask:0xf
	ds_read_b128 v[56:59], v0 offset:16384
	ds_read_b128 v[40:43], v0 offset:15360
	v_add_f32_dpp v94, v93, v93 row_ror:8 row_mask:0xf bank_mask:0xf
	v_add_f32_dpp v110, v93, v93 row_ror:8 row_mask:0xf bank_mask:0x2
	ds_read_b128 v[52:55], v0 offset:16128
	v_pk_fma_f32 v[4:5], v[94:95], v[72:73], v[96:97] op_sel_hi:[0,1,1] neg_lo:[1,0,0] neg_hi:[1,0,0]
	v_pk_fma_f32 v[6:7], v[94:95], v[74:75], v[98:99] op_sel_hi:[0,1,1] neg_lo:[1,0,0] neg_hi:[1,0,0]
	s_waitcnt lgkmcnt(6)
; __device__ __forceinline__ void rwkv_scan2_item(const Params& p, int item, char* ldsraw) {
;     ...
;         R_LOAD(0)
;         float sakA = 0.f, sakB = 0.f;
; #pragma unroll
;         for (int q = 0; q < 16; q++) {
;           const f32x4 cw = nw, ckk = nkk, ckka = nkka, ck = nk; const float cvA = nvA, cvB = nvB;
;           if (q < 15) R_LOAD(q + 1)
;           __builtin_amdgcn_sched_barrier(0);
;           float mA0 = mul_s(a0, ckk.x), mA1 = mul_s(a2, ckk.z), mB0 = mul_s(b0, ckk.x), mB1 = mul_s(b2, ckk.z);
;           mA0 = fma_s(a1, ckk.y, mA0); mA1 = fma_s(a3, ckk.w, mA1); mB0 = fma_s(b1, ckk.y, mB0); mB1 = fma_s(b3, ckk.w, mB1);
;           float psA = add_s(mA0, mA1), psB = add_s(mB0, mB1);
;           psA = row16_sum(psA); psB = row16_sum(psB);
;           { const float t0 = fnma_s(psA, ckka.x, mul_s(cvA, ck.x)), t1 = fnma_s(psA, ckka.y, mul_s(cvA, ck.y));
;             const float t2 = fnma_s(psA, ckka.z, mul_s(cvA, ck.z)), t3 = fnma_s(psA, ckka.w, mul_s(cvA, ck.w));
;             a0 = fma_s(a0, cw.x, t0); a1 = fma_s(a1, cw.y, t1); a2 = fma_s(a2, cw.z, t2); a3 = fma_s(a3, cw.w, t3); }
;           { const float t0 = fnma_s(psB, ckka.x, mul_s(cvB, ck.x)), t1 = fnma_s(psB, ckka.y, mul_s(cvB, ck.y));
;             const float t2 = fnma_s(psB, ckka.z, mul_s(cvB, ck.z)), t3 = fnma_s(psB, ckka.w, mul_s(cvB, ck.w));
;             b0 = fma_s(b0, cw.x, t0); b1 = fma_s(b1, cw.y, t1); b2 = fma_s(b2, cw.z, t2); b3 = fma_s(b3, cw.w, t3); }
;           sakA = sel_eq(sakA, psA, jl, q); sakB = sel_eq(sakB, psB, jl, q);
;         }
;     ...
;         SA[(c & 1) * 256 + jl * 16 + row8] = sakA; SA[(c & 1) * 256 + jl * 16 + 8 + row8] = sakB;
;       }
;     } else {
;       if (c >= 1) {
;         const float* d = buf + bprev * CH + jl * 4;
;         const float* dvp = buf + bprev * CH + 320 + row8;
;         const float* dcp = buf + bprev * CH + 336;
;         const float* sap = SA + ((c - 1) & 1) * 256 + row8;
;         f32x4 nw, nkka, nk, nwr; float nvA, nvB, nsA, nsB; f32x2 ncc;
;     ...
;         Y_LOAD(0)
;         float ykA = 0.f, ykB = 0.f;
; #pragma unroll
;         for (int q = 0; q < 16; q++) {
;           const f32x4 cw = nw, ckka = nkka, ck = nk, cwr = nwr; const float cvA = nvA, cvB = nvB, psA = nsA, psB = nsB; const f32x2 ccc = ncc;
;           if (q < 15) Y_LOAD(q + 1)
;           __builtin_amdgcn_sched_barrier(0);
	v_pk_mul_f32 v[88:89], v[4:5], v[142:143] op_sel_hi:[0,1]
	v_pk_mul_f32 v[90:91], v[6:7], v[146:147] op_sel_hi:[0,1]
	v_pk_fma_f32 v[88:89], v[4:5], v[144:145], v[88:89] op_sel:[1,0,0] op_sel_hi:[1,1,1]
	v_pk_fma_f32 v[90:91], v[6:7], v[148:149], v[90:91] op_sel:[1,0,0] op_sel_hi:[1,1,1]
	v_pk_add_f32 v[102:103], v[88:89], v[90:91]
	v_pk_mul_f32 v[96:97], v[82:83], v[154:155] op_sel:[1,0] op_sel_hi:[1,1]
	v_pk_mul_f32 v[98:99], v[82:83], v[156:157] op_sel:[1,0] op_sel_hi:[1,1]
	v_add_f32_dpp v93, v102, v102 quad_perm:[1,0,3,2] row_mask:0xf bank_mask:0xf
	v_pk_fma_f32 v[96:97], v[4:5], v[138:139], v[96:97]
	v_pk_fma_f32 v[98:99], v[6:7], v[140:141], v[98:99]
	v_add_f32_dpp v92, v93, v93 quad_perm:[2,3,0,1] row_mask:0xf bank_mask:0xf
	ds_read_b128 v[64:67], v0 offset:16896
	ds_read_b128 v[68:71], v0 offset:17152
	v_add_f32_dpp v93, v92, v92 row_ror:4 row_mask:0xf bank_mask:0xf
	ds_read_b128 v[76:79], v0 offset:17664
	ds_read_b128 v[60:63], v0 offset:16640
	v_add_f32_dpp v94, v93, v93 row_ror:8 row_mask:0xf bank_mask:0xf
	v_add_f32_dpp v110, v93, v93 row_ror:8 row_mask:0xf bank_mask:0x8
	ds_read_b128 v[72:75], v0 offset:17408
	v_pk_fma_f32 v[4:5], v[94:95], v[150:151], v[96:97] op_sel_hi:[0,1,1] neg_lo:[1,0,0] neg_hi:[1,0,0]
	v_pk_fma_f32 v[6:7], v[94:95], v[152:153], v[98:99] op_sel_hi:[0,1,1] neg_lo:[1,0,0] neg_hi:[1,0,0]
	v_add_f32_dpp v133, v133, v133 row_ror:8 row_mask:0xf bank_mask:0x3
	s_nop 1
	v_add_f32_dpp v133, v103, v103 row_ror:8 row_mask:0xf bank_mask:0xc
	v_add_f32_dpp v105, v105, v105 row_half_mirror row_mask:0xf bank_mask:0x5
	s_nop 1
	v_add_f32_dpp v105, v133, v133 row_half_mirror row_mask:0xf bank_mask:0xa
	s_waitcnt lgkmcnt(5)
	v_pk_mul_f32 v[88:89], v[4:5], v[44:45] op_sel_hi:[0,1]
	v_pk_mul_f32 v[90:91], v[6:7], v[48:49] op_sel_hi:[0,1]
	v_pk_fma_f32 v[88:89], v[4:5], v[46:47], v[88:89] op_sel:[1,0,0] op_sel_hi:[1,1,1]
	v_pk_fma_f32 v[90:91], v[6:7], v[50:51], v[90:91] op_sel:[1,0,0] op_sel_hi:[1,1,1]
	v_pk_add_f32 v[134:135], v[88:89], v[90:91]
	v_pk_mul_f32 v[96:97], v[84:85], v[56:57] op_sel:[0,0] op_sel_hi:[0,1]
	v_pk_mul_f32 v[98:99], v[84:85], v[58:59] op_sel:[0,0] op_sel_hi:[0,1]
	v_add_f32_dpp v93, v134, v134 quad_perm:[1,0,3,2] row_mask:0xf bank_mask:0xf
	v_pk_fma_f32 v[96:97], v[4:5], v[40:41], v[96:97]
	v_pk_fma_f32 v[98:99], v[6:7], v[42:43], v[98:99]
	v_add_f32_dpp v92, v93, v93 quad_perm:[2,3,0,1] row_mask:0xf bank_mask:0xf
	ds_read_b128 v[142:145], v0 offset:18176
	ds_read_b128 v[146:149], v0 offset:18432
	v_add_f32_dpp v93, v92, v92 row_ror:4 row_mask:0xf bank_mask:0xf
	ds_read_b128 v[154:157], v0 offset:18944
	ds_read_b128 v[138:141], v0 offset:17920
	v_add_f32_dpp v94, v93, v93 row_ror:8 row_mask:0xf bank_mask:0xf
	v_add_f32_dpp v111, v93, v93 row_ror:8 row_mask:0xf bank_mask:0x1
	ds_read_b128 v[150:153], v0 offset:18688
	v_pk_fma_f32 v[4:5], v[94:95], v[52:53], v[96:97] op_sel_hi:[0,1,1] neg_lo:[1,0,0] neg_hi:[1,0,0]
	v_pk_fma_f32 v[6:7], v[94:95], v[54:55], v[98:99] op_sel_hi:[0,1,1] neg_lo:[1,0,0] neg_hi:[1,0,0]
	s_waitcnt lgkmcnt(5)
	v_pk_mul_f32 v[88:89], v[4:5], v[64:65] op_sel_hi:[0,1]
	v_pk_mul_f32 v[90:91], v[6:7], v[68:69] op_sel_hi:[0,1]
	v_pk_fma_f32 v[88:89], v[4:5], v[66:67], v[88:89] op_sel:[1,0,0] op_sel_hi:[1,1,1]
	v_pk_fma_f32 v[90:91], v[6:7], v[70:71], v[90:91] op_sel:[1,0,0] op_sel_hi:[1,1,1]
	v_pk_add_f32 v[136:137], v[88:89], v[90:91]
	v_pk_mul_f32 v[96:97], v[84:85], v[76:77] op_sel:[1,0] op_sel_hi:[1,1]
	v_pk_mul_f32 v[98:99], v[84:85], v[78:79] op_sel:[1,0] op_sel_hi:[1,1]
	v_add_f32_dpp v93, v136, v136 quad_perm:[1,0,3,2] row_mask:0xf bank_mask:0xf
	v_pk_fma_f32 v[96:97], v[4:5], v[60:61], v[96:97]
	v_pk_fma_f32 v[98:99], v[6:7], v[62:63], v[98:99]
	v_add_f32_dpp v92, v93, v93 quad_perm:[2,3,0,1] row_mask:0xf bank_mask:0xf
	ds_read_b128 v[44:47], v0 offset:19456
	ds_read_b128 v[48:51], v0 offset:19712
	v_add_f32_dpp v93, v92, v92 row_ror:4 row_mask:0xf bank_mask:0xf
	ds_read_b128 v[56:59], v0 offset:20224
	ds_read_b128 v[40:43], v0 offset:19200
	v_add_f32_dpp v94, v93, v93 row_ror:8 row_mask:0xf bank_mask:0xf
	v_add_f32_dpp v111, v93, v93 row_ror:8 row_mask:0xf bank_mask:0x4
	ds_read_b128 v[52:55], v0 offset:19968
	v_pk_fma_f32 v[4:5], v[94:95], v[72:73], v[96:97] op_sel_hi:[0,1,1] neg_lo:[1,0,0] neg_hi:[1,0,0]
	v_pk_fma_f32 v[6:7], v[94:95], v[74:75], v[98:99] op_sel_hi:[0,1,1] neg_lo:[1,0,0] neg_hi:[1,0,0]
	ds_read_b32 v112, v10 offset:0
	ds_read_b64 v[114:115], v11 offset:0
	v_add_f32_dpp v135, v135, v135 row_ror:8 row_mask:0xf bank_mask:0x3
	s_nop 1
	v_add_f32_dpp v135, v137, v137 row_ror:8 row_mask:0xf bank_mask:0xc
	s_waitcnt lgkmcnt(7)
	v_pk_mul_f32 v[88:89], v[4:5], v[142:143] op_sel_hi:[0,1]
	v_pk_mul_f32 v[90:91], v[6:7], v[146:147] op_sel_hi:[0,1]
	v_pk_fma_f32 v[88:89], v[4:5], v[144:145], v[88:89] op_sel:[1,0,0] op_sel_hi:[1,1,1]
	v_pk_fma_f32 v[90:91], v[6:7], v[148:149], v[90:91] op_sel:[1,0,0] op_sel_hi:[1,1,1]
	v_pk_add_f32 v[102:103], v[88:89], v[90:91]
	v_pk_mul_f32 v[96:97], v[86:87], v[154:155] op_sel:[0,0] op_sel_hi:[0,1]
	v_pk_mul_f32 v[98:99], v[86:87], v[156:157] op_sel:[0,0] op_sel_hi:[0,1]
	v_add_f32_dpp v93, v102, v102 quad_perm:[1,0,3,2] row_mask:0xf bank_mask:0xf
	v_pk_fma_f32 v[96:97], v[4:5], v[138:139], v[96:97]
	v_pk_fma_f32 v[98:99], v[6:7], v[140:141], v[98:99]
	v_add_f32_dpp v92, v93, v93 quad_perm:[2,3,0,1] row_mask:0xf bank_mask:0xf
	s_nop 1
	v_add_f32_dpp v93, v92, v92 row_ror:4 row_mask:0xf bank_mask:0xf
	s_nop 1
	v_add_f32_dpp v94, v93, v93 row_ror:8 row_mask:0xf bank_mask:0xf
	v_add_f32_dpp v111, v93, v93 row_ror:8 row_mask:0xf bank_mask:0x2
	v_pk_fma_f32 v[4:5], v[94:95], v[150:151], v[96:97] op_sel_hi:[0,1,1] neg_lo:[1,0,0] neg_hi:[1,0,0]
	v_pk_fma_f32 v[6:7], v[94:95], v[152:153], v[98:99] op_sel_hi:[0,1,1] neg_lo:[1,0,0] neg_hi:[1,0,0]
	s_waitcnt lgkmcnt(2)
; __device__ __forceinline__ float bf2f(unsigned short b) { return __uint_as_float(((unsigned)b) << 16); }
; __device__ __forceinline__ unsigned short f2bf(float f) { unsigned r; asm("v_cvt_pk_bf16_f32 %0, %1, %1" : "=v"(r) : "v"(f)); return (unsigned short)(r & 0xffffu); }
; __device__ __forceinline__ float bflo(unsigned u) { return __uint_as_float(u << 16); }
; __device__ __forceinline__ float bfhi(unsigned u) { return __uint_as_float(u & 0xffff0000u); }
; __device__ __forceinline__ float fma_s(float a, float b, float c) { float d; asm("v_fma_f32 %0, %1, %2, %3" : "=v"(d) : "v"(a), "v"(b), "v"(c)); return d; }
; __device__ __forceinline__ void rwkv_scan2_item(const Params& p, int item, char* ldsraw) {
;     ...
;   auto load = [&](int chunk) {
;     const size_t base = (size_t)bh * S + chunk * 16 + st;
;     pw = *(const f32x4*)(RW + base * 64 + part * 4);
;     const bf16_t* rb = RB + base * 320;
;     pkk = *(const u32x2*)(rb + part * 4); pkka = *(const u32x2*)(rb + 64 + part * 4);
;     pk = *(const u32x2*)(rb + 128 + part * 4); pwr = *(const u32x2*)(rb + 192 + part * 4);
;     pv = rb[256 + r16 * 16 + part];
;     pc = (part < 2) ? RC[base * 4 + part] : 0.f;
;   };
;   auto store = [&](int bi) {
;     float* d = buf + bi * CH + st * STEP;
;     *(f32x4*)(d + part * 4) = pw;
;     *(f32x4*)(d + 64 + part * 4) = (f32x4){bflo(pkk[0]), bfhi(pkk[0]), bflo(pkk[1]), bfhi(pkk[1])};
;     *(f32x4*)(d + 128 + part * 4) = (f32x4){bflo(pkka[0]), bfhi(pkka[0]), bflo(pkka[1]), bfhi(pkka[1])};
;     *(f32x4*)(d + 192 + part * 4) = (f32x4){bflo(pk[0]), bfhi(pk[0]), bflo(pk[1]), bfhi(pk[1])};
;     *(f32x4*)(d + 256 + part * 4) = (f32x4){bflo(pwr[0]), bfhi(pwr[0]), bflo(pwr[1]), bfhi(pwr[1])};
;     d[320 + part] = ident ? 0.f : bf2f(pv);
;     if (part < 2) d[336 + part] = pc;
;   };
;     ...
;           const float yA = fnma_s(psA, ccc.x, fma_s(cvA, ccc.y, puA)), yB = fnma_s(psB, ccc.x, fma_s(cvB, ccc.y, puB));
;           ykA = sel_eq(ykA, yA, jl, q); ykB = sel_eq(ykB, yB, jl, q);
;         }
;     ...
;         yout[(size_t)(c - 1) * ystride] = f2bf(ykA); yout[(size_t)(c - 1) * ystride + 8] = f2bf(ykB);
;       }
;     }
;     if (c + 1 < 128) store(bnext);
;     bi = bnext;
;     asm volatile("s_waitcnt lgkmcnt(0)" ::: "memory"); __builtin_amdgcn_s_barrier(); asm volatile("" ::: "memory");
	v_pk_mul_f32 v[88:89], v[4:5], v[44:45] op_sel_hi:[0,1]
	v_pk_mul_f32 v[90:91], v[6:7], v[48:49] op_sel_hi:[0,1]
	v_pk_fma_f32 v[88:89], v[4:5], v[46:47], v[88:89] op_sel:[1,0,0] op_sel_hi:[1,1,1]
	v_pk_fma_f32 v[90:91], v[6:7], v[50:51], v[90:91] op_sel:[1,0,0] op_sel_hi:[1,1,1]
	v_pk_add_f32 v[132:133], v[88:89], v[90:91]
	v_pk_mul_f32 v[96:97], v[86:87], v[56:57] op_sel:[1,0] op_sel_hi:[1,1]
	v_pk_mul_f32 v[98:99], v[86:87], v[58:59] op_sel:[1,0] op_sel_hi:[1,1]
	v_add_f32_dpp v93, v132, v132 quad_perm:[1,0,3,2] row_mask:0xf bank_mask:0xf
	v_pk_fma_f32 v[96:97], v[4:5], v[40:41], v[96:97]
	v_pk_fma_f32 v[98:99], v[6:7], v[42:43], v[98:99]
	v_add_f32_dpp v92, v93, v93 quad_perm:[2,3,0,1] row_mask:0xf bank_mask:0xf
	s_nop 1
	v_add_f32_dpp v93, v92, v92 row_ror:4 row_mask:0xf bank_mask:0xf
	s_nop 1
	v_add_f32_dpp v94, v93, v93 row_ror:8 row_mask:0xf bank_mask:0xf
	v_add_f32_dpp v111, v93, v93 row_ror:8 row_mask:0xf bank_mask:0x8
	v_pk_fma_f32 v[4:5], v[94:95], v[52:53], v[96:97] op_sel_hi:[0,1,1] neg_lo:[1,0,0] neg_hi:[1,0,0]
	v_pk_fma_f32 v[6:7], v[94:95], v[54:55], v[98:99] op_sel_hi:[0,1,1] neg_lo:[1,0,0] neg_hi:[1,0,0]
	v_add_f32_dpp v103, v103, v103 row_ror:8 row_mask:0xf bank_mask:0x3
	s_nop 1
	v_add_f32_dpp v103, v133, v133 row_ror:8 row_mask:0xf bank_mask:0xc
	v_add_f32_dpp v135, v135, v135 row_half_mirror row_mask:0xf bank_mask:0x5
	s_nop 1
	v_add_f32_dpp v135, v103, v103 row_half_mirror row_mask:0xf bank_mask:0xa
	v_cndmask_b32_e64 v106, v135, v105, s[36:37]
	v_cndmask_b32_e64 v107, v105, v135, s[36:37]
	s_nop 1
	v_add_f32_dpp v105, v106, v107 quad_perm:[2,3,0,1] row_mask:0xf bank_mask:0xf
	v_cndmask_b32_e64 v106, v105, v101, s[34:35]
	v_cndmask_b32_e64 v107, v101, v105, s[34:35]
	s_nop 1
	v_add_f32_dpp v101, v106, v107 quad_perm:[1,0,3,2] row_mask:0xf bank_mask:0xf
	v_cndmask_b32_e64 v106, v108, v110, s[34:35]
	v_cndmask_b32_e64 v107, v109, v111, s[34:35]
	v_cndmask_b32_e64 v106, v106, v107, s[36:37]
	s_waitcnt lgkmcnt(0)
	v_fma_f32 v101, v112, v115, v101
	v_fma_f32 v101, -v106, v114, v101
	v_cvt_pk_bf16_f32 v107, v101, v101
	global_store_short v16, v107, s[30:31]
	s_waitcnt vmcnt(1)
	ds_write_b128 v2, v[20:23] offset:21632
	v_lshlrev_b32_e32 v36, 16, v24
	v_lshlrev_b32_e32 v37, 16, v30
	v_and_b32_e32 v38, 0xffff0000, v24
	v_and_b32_e32 v39, 0xffff0000, v30
	ds_write_b128 v2, v[36:39] offset:21888
	v_lshlrev_b32_e32 v40, 16, v25
	v_lshlrev_b32_e32 v41, 16, v31
	v_and_b32_e32 v42, 0xffff0000, v25
	v_and_b32_e32 v43, 0xffff0000, v31
	ds_write_b128 v2, v[40:43] offset:22144
	v_lshlrev_b32_e32 v44, 16, v26
	v_and_b32_e32 v45, 0xffff0000, v26
	v_lshlrev_b32_e32 v46, 16, v27
	v_and_b32_e32 v47, 0xffff0000, v27
	ds_write_b128 v2, v[44:47] offset:22400
	v_lshlrev_b32_e32 v48, 16, v28
	v_and_b32_e32 v49, 0xffff0000, v28
	v_lshlrev_b32_e32 v50, 16, v29
	v_and_b32_e32 v51, 0xffff0000, v29
	ds_write_b128 v2, v[48:51] offset:22656
	v_lshlrev_b32_e32 v52, 16, v32
	s_cmp_eq_u32 s41, 2
	s_cselect_b32 s2, 0, -1
	v_and_b32_e32 v52, s2, v52
	ds_write_b32 v8, v52 offset:21632
	s_mov_b32 s2, 0x00010001
	s_mov_b32 s3, 0x00010001
	s_mov_b64 exec, s[2:3]
	ds_write_b64 v9, v[34:35] offset:21632
	s_mov_b64 exec, -1
	s_add_u32 s24, s24, 0x1000
	s_addc_u32 s25, s25, 0
	s_add_u32 s26, s26, 0x2800
	s_addc_u32 s27, s27, 0
	s_add_u32 s28, s28, 0x100
	s_addc_u32 s29, s29, 0
	s_add_u32 s30, s30, s40
	s_addc_u32 s31, s31, 0
	s_waitcnt lgkmcnt(0)
	s_barrier
	s_cmp_eq_u32 s38, 63
	s_cbranch_scc1 .Lsc_o_nold
	global_load_dwordx4 v[20:23], v12, s[24:25]
	global_load_dwordx2 v[24:25], v13, s[26:27]
	global_load_dwordx2 v[26:27], v13, s[26:27] offset:128
	global_load_dwordx2 v[28:29], v13, s[26:27] offset:256
	global_load_dwordx2 v[30:31], v13, s[26:27] offset:384
	global_load_ushort v32, v14, s[26:27]
	global_load_dwordx2 v[34:35], v15, s[28:29]
.Lsc_o_nold:
	ds_read_b128 v[44:47], v0 offset:21888
	ds_read_b128 v[48:51], v0 offset:22144
	ds_read_b128 v[56:59], v0 offset:22656
	ds_read_b128 v[40:43], v0 offset:21632
	ds_read_b128 v[52:55], v0 offset:22400
	ds_read_b128 v[80:83], v1 offset:21632
	ds_read_b128 v[64:67], v0 offset:23168
	ds_read_b128 v[68:71], v0 offset:23424
	ds_read_b128 v[76:79], v0 offset:23936
	ds_read_b128 v[60:63], v0 offset:22912
	ds_read_b128 v[72:75], v0 offset:23680
	s_waitcnt lgkmcnt(5)
	v_pk_mul_f32 v[88:89], v[4:5], v[44:45] op_sel_hi:[0,1]
	v_pk_mul_f32 v[90:91], v[6:7], v[48:49] op_sel_hi:[0,1]
	v_pk_fma_f32 v[88:89], v[4:5], v[46:47], v[88:89] op_sel:[1,0,0] op_sel_hi:[1,1,1]
	v_pk_fma_f32 v[90:91], v[6:7], v[50:51], v[90:91] op_sel:[1,0,0] op_sel_hi:[1,1,1]
	v_pk_add_f32 v[100:101], v[88:89], v[90:91]
	v_pk_mul_f32 v[96:97], v[80:81], v[56:57] op_sel:[0,0] op_sel_hi:[0,1]
	v_pk_mul_f32 v[98:99], v[80:81], v[58:59] op_sel:[0,0] op_sel_hi:[0,1]
	v_add_f32_dpp v93, v100, v100 quad_perm:[1,0,3,2] row_mask:0xf bank_mask:0xf
	v_pk_fma_f32 v[96:97], v[4:5], v[40:41], v[96:97]
	v_pk_fma_f32 v[98:99], v[6:7], v[42:43], v[98:99]
	v_add_f32_dpp v92, v93, v93 quad_perm:[2,3,0,1] row_mask:0xf bank_mask:0xf
	ds_read_b128 v[142:145], v0 offset:24448
	ds_read_b128 v[146:149], v0 offset:24704
	v_add_f32_dpp v93, v92, v92 row_ror:4 row_mask:0xf bank_mask:0xf
	ds_read_b128 v[154:157], v0 offset:25216
	ds_read_b128 v[138:141], v0 offset:24192
	v_add_f32_dpp v94, v93, v93 row_ror:8 row_mask:0xf bank_mask:0xf
	v_add_f32_dpp v108, v93, v93 row_ror:8 row_mask:0xf bank_mask:0x1
	ds_read_b128 v[150:153], v0 offset:24960
	v_pk_fma_f32 v[4:5], v[94:95], v[52:53], v[96:97] op_sel_hi:[0,1,1] neg_lo:[1,0,0] neg_hi:[1,0,0]
	v_pk_fma_f32 v[6:7], v[94:95], v[54:55], v[98:99] op_sel_hi:[0,1,1] neg_lo:[1,0,0] neg_hi:[1,0,0]
	s_waitcnt lgkmcnt(5)
; __device__ __forceinline__ void rwkv_scan2_item(const Params& p, int item, char* ldsraw) {
;     ...
;         R_LOAD(0)
;         float sakA = 0.f, sakB = 0.f;
; #pragma unroll
;         for (int q = 0; q < 16; q++) {
;           const f32x4 cw = nw, ckk = nkk, ckka = nkka, ck = nk; const float cvA = nvA, cvB = nvB;
;           if (q < 15) R_LOAD(q + 1)
;           __builtin_amdgcn_sched_barrier(0);
;           float mA0 = mul_s(a0, ckk.x), mA1 = mul_s(a2, ckk.z), mB0 = mul_s(b0, ckk.x), mB1 = mul_s(b2, ckk.z);
;           mA0 = fma_s(a1, ckk.y, mA0); mA1 = fma_s(a3, ckk.w, mA1); mB0 = fma_s(b1, ckk.y, mB0); mB1 = fma_s(b3, ckk.w, mB1);
;           float psA = add_s(mA0, mA1), psB = add_s(mB0, mB1);
;           psA = row16_sum(psA); psB = row16_sum(psB);
;           { const float t0 = fnma_s(psA, ckka.x, mul_s(cvA, ck.x)), t1 = fnma_s(psA, ckka.y, mul_s(cvA, ck.y));
;             const float t2 = fnma_s(psA, ckka.z, mul_s(cvA, ck.z)), t3 = fnma_s(psA, ckka.w, mul_s(cvA, ck.w));
;             a0 = fma_s(a0, cw.x, t0); a1 = fma_s(a1, cw.y, t1); a2 = fma_s(a2, cw.z, t2); a3 = fma_s(a3, cw.w, t3); }
;           { const float t0 = fnma_s(psB, ckka.x, mul_s(cvB, ck.x)), t1 = fnma_s(psB, ckka.y, mul_s(cvB, ck.y));
;             const float t2 = fnma_s(psB, ckka.z, mul_s(cvB, ck.z)), t3 = fnma_s(psB, ckka.w, mul_s(cvB, ck.w));
;             b0 = fma_s(b0, cw.x, t0); b1 = fma_s(b1, cw.y, t1); b2 = fma_s(b2, cw.z, t2); b3 = fma_s(b3, cw.w, t3); }
;           sakA = sel_eq(sakA, psA, jl, q); sakB = sel_eq(sakB, psB, jl, q);
;         }
;     ...
;         SA[(c & 1) * 256 + jl * 16 + row8] = sakA; SA[(c & 1) * 256 + jl * 16 + 8 + row8] = sakB;
;       }
;     } else {
;       if (c >= 1) {
;         const float* d = buf + bprev * CH + jl * 4;
;         const float* dvp = buf + bprev * CH + 320 + row8;
;         const float* dcp = buf + bprev * CH + 336;
;         const float* sap = SA + ((c - 1) & 1) * 256 + row8;
;         f32x4 nw, nkka, nk, nwr; float nvA, nvB, nsA, nsB; f32x2 ncc;
;     ...
;         Y_LOAD(0)
;         float ykA = 0.f, ykB = 0.f;
; #pragma unroll
;         for (int q = 0; q < 16; q++) {
;           const f32x4 cw = nw, ckka = nkka, ck = nk, cwr = nwr; const float cvA = nvA, cvB = nvB, psA = nsA, psB = nsB; const f32x2 ccc = ncc;
;           if (q < 15) Y_LOAD(q + 1)
;           __builtin_amdgcn_sched_barrier(0);
	v_pk_mul_f32 v[88:89], v[4:5], v[64:65] op_sel_hi:[0,1]
	v_pk_mul_f32 v[90:91], v[6:7], v[68:69] op_sel_hi:[0,1]
	v_pk_fma_f32 v[88:89], v[4:5], v[66:67], v[88:89] op_sel:[1,0,0] op_sel_hi:[1,1,1]
	v_pk_fma_f32 v[90:91], v[6:7], v[70:71], v[90:91] op_sel:[1,0,0] op_sel_hi:[1,1,1]
	v_pk_add_f32 v[102:103], v[88:89], v[90:91]
	v_pk_mul_f32 v[96:97], v[80:81], v[76:77] op_sel:[1,0] op_sel_hi:[1,1]
	v_pk_mul_f32 v[98:99], v[80:81], v[78:79] op_sel:[1,0] op_sel_hi:[1,1]
	v_add_f32_dpp v93, v102, v102 quad_perm:[1,0,3,2] row_mask:0xf bank_mask:0xf
	v_pk_fma_f32 v[96:97], v[4:5], v[60:61], v[96:97]
	v_pk_fma_f32 v[98:99], v[6:7], v[62:63], v[98:99]
	v_add_f32_dpp v92, v93, v93 quad_perm:[2,3,0,1] row_mask:0xf bank_mask:0xf
	ds_read_b128 v[44:47], v0 offset:25728
	ds_read_b128 v[48:51], v0 offset:25984
	v_add_f32_dpp v93, v92, v92 row_ror:4 row_mask:0xf bank_mask:0xf
	ds_read_b128 v[56:59], v0 offset:26496
	ds_read_b128 v[40:43], v0 offset:25472
	v_add_f32_dpp v94, v93, v93 row_ror:8 row_mask:0xf bank_mask:0xf
	v_add_f32_dpp v108, v93, v93 row_ror:8 row_mask:0xf bank_mask:0x4
	ds_read_b128 v[52:55], v0 offset:26240
	v_pk_fma_f32 v[4:5], v[94:95], v[72:73], v[96:97] op_sel_hi:[0,1,1] neg_lo:[1,0,0] neg_hi:[1,0,0]
	v_pk_fma_f32 v[6:7], v[94:95], v[74:75], v[98:99] op_sel_hi:[0,1,1] neg_lo:[1,0,0] neg_hi:[1,0,0]
	ds_read_b128 v[84:87], v1 offset:21648
	v_add_f32_dpp v101, v101, v101 row_ror:8 row_mask:0xf bank_mask:0x3
	s_nop 1
	v_add_f32_dpp v101, v103, v103 row_ror:8 row_mask:0xf bank_mask:0xc
	s_waitcnt lgkmcnt(6)
	v_pk_mul_f32 v[88:89], v[4:5], v[142:143] op_sel_hi:[0,1]
	v_pk_mul_f32 v[90:91], v[6:7], v[146:147] op_sel_hi:[0,1]
	v_pk_fma_f32 v[88:89], v[4:5], v[144:145], v[88:89] op_sel:[1,0,0] op_sel_hi:[1,1,1]
	v_pk_fma_f32 v[90:91], v[6:7], v[148:149], v[90:91] op_sel:[1,0,0] op_sel_hi:[1,1,1]
	v_pk_add_f32 v[104:105], v[88:89], v[90:91]
	v_pk_mul_f32 v[96:97], v[82:83], v[154:155] op_sel:[0,0] op_sel_hi:[0,1]
	v_pk_mul_f32 v[98:99], v[82:83], v[156:157] op_sel:[0,0] op_sel_hi:[0,1]
	v_add_f32_dpp v93, v104, v104 quad_perm:[1,0,3,2] row_mask:0xf bank_mask:0xf
	v_pk_fma_f32 v[96:97], v[4:5], v[138:139], v[96:97]
	v_pk_fma_f32 v[98:99], v[6:7], v[140:141], v[98:99]
	v_add_f32_dpp v92, v93, v93 quad_perm:[2,3,0,1] row_mask:0xf bank_mask:0xf
	ds_read_b128 v[64:67], v0 offset:27008
	ds_read_b128 v[68:71], v0 offset:27264
	v_add_f32_dpp v93, v92, v92 row_ror:4 row_mask:0xf bank_mask:0xf
	ds_read_b128 v[76:79], v0 offset:27776
	ds_read_b128 v[60:63], v0 offset:26752
	v_add_f32_dpp v94, v93, v93 row_ror:8 row_mask:0xf bank_mask:0xf
	v_add_f32_dpp v108, v93, v93 row_ror:8 row_mask:0xf bank_mask:0x2
	ds_read_b128 v[72:75], v0 offset:27520
	v_pk_fma_f32 v[4:5], v[94:95], v[150:151], v[96:97] op_sel_hi:[0,1,1] neg_lo:[1,0,0] neg_hi:[1,0,0]
	v_pk_fma_f32 v[6:7], v[94:95], v[152:153], v[98:99] op_sel_hi:[0,1,1] neg_lo:[1,0,0] neg_hi:[1,0,0]
	s_waitcnt lgkmcnt(6)
	v_pk_mul_f32 v[88:89], v[4:5], v[44:45] op_sel_hi:[0,1]
	v_pk_mul_f32 v[90:91], v[6:7], v[48:49] op_sel_hi:[0,1]
	v_pk_fma_f32 v[88:89], v[4:5], v[46:47], v[88:89] op_sel:[1,0,0] op_sel_hi:[1,1,1]
	v_pk_fma_f32 v[90:91], v[6:7], v[50:51], v[90:91] op_sel:[1,0,0] op_sel_hi:[1,1,1]
	v_pk_add_f32 v[132:133], v[88:89], v[90:91]
	v_pk_mul_f32 v[96:97], v[82:83], v[56:57] op_sel:[1,0] op_sel_hi:[1,1]
	v_pk_mul_f32 v[98:99], v[82:83], v[58:59] op_sel:[1,0] op_sel_hi:[1,1]
	v_add_f32_dpp v93, v132, v132 quad_perm:[1,0,3,2] row_mask:0xf bank_mask:0xf
	v_pk_fma_f32 v[96:97], v[4:5], v[40:41], v[96:97]
	v_pk_fma_f32 v[98:99], v[6:7], v[42:43], v[98:99]
	v_add_f32_dpp v92, v93, v93 quad_perm:[2,3,0,1] row_mask:0xf bank_mask:0xf
	ds_read_b128 v[142:145], v0 offset:28288
	ds_read_b128 v[146:149], v0 offset:28544
	v_add_f32_dpp v93, v92, v92 row_ror:4 row_mask:0xf bank_mask:0xf
	ds_read_b128 v[154:157], v0 offset:29056
	ds_read_b128 v[138:141], v0 offset:28032
	v_add_f32_dpp v94, v93, v93 row_ror:8 row_mask:0xf bank_mask:0xf
	v_add_f32_dpp v108, v93, v93 row_ror:8 row_mask:0xf bank_mask:0x8
	ds_read_b128 v[150:153], v0 offset:28800
	v_pk_fma_f32 v[4:5], v[94:95], v[52:53], v[96:97] op_sel_hi:[0,1,1] neg_lo:[1,0,0] neg_hi:[1,0,0]
	v_pk_fma_f32 v[6:7], v[94:95], v[54:55], v[98:99] op_sel_hi:[0,1,1] neg_lo:[1,0,0] neg_hi:[1,0,0]
	v_add_f32_dpp v105, v105, v105 row_ror:8 row_mask:0xf bank_mask:0x3
	s_nop 1
	v_add_f32_dpp v105, v133, v133 row_ror:8 row_mask:0xf bank_mask:0xc
	v_add_f32_dpp v101, v101, v101 row_half_mirror row_mask:0xf bank_mask:0x5
	s_nop 1
	v_add_f32_dpp v101, v105, v105 row_half_mirror row_mask:0xf bank_mask:0xa
	s_waitcnt lgkmcnt(5)
	v_pk_mul_f32 v[88:89], v[4:5], v[64:65] op_sel_hi:[0,1]
	v_pk_mul_f32 v[90:91], v[6:7], v[68:69] op_sel_hi:[0,1]
	v_pk_fma_f32 v[88:89], v[4:5], v[66:67], v[88:89] op_sel:[1,0,0] op_sel_hi:[1,1,1]
	v_pk_fma_f32 v[90:91], v[6:7], v[70:71], v[90:91] op_sel:[1,0,0] op_sel_hi:[1,1,1]
	v_pk_add_f32 v[134:135], v[88:89], v[90:91]
	v_pk_mul_f32 v[96:97], v[84:85], v[76:77] op_sel:[0,0] op_sel_hi:[0,1]
	v_pk_mul_f32 v[98:99], v[84:85], v[78:79] op_sel:[0,0] op_sel_hi:[0,1]
	v_add_f32_dpp v93, v134, v134 quad_perm:[1,0,3,2] row_mask:0xf bank_mask:0xf
	v_pk_fma_f32 v[96:97], v[4:5], v[60:61], v[96:97]
	v_pk_fma_f32 v[98:99], v[6:7], v[62:63], v[98:99]
	v_add_f32_dpp v92, v93, v93 quad_perm:[2,3,0,1] row_mask:0xf bank_mask:0xf
	ds_read_b128 v[44:47], v0 offset:29568
	ds_read_b128 v[48:51], v0 offset:29824
	v_add_f32_dpp v93, v92, v92 row_ror:4 row_mask:0xf bank_mask:0xf
	ds_read_b128 v[56:59], v0 offset:30336
	ds_read_b128 v[40:43], v0 offset:29312
	v_add_f32_dpp v94, v93, v93 row_ror:8 row_mask:0xf bank_mask:0xf
	v_add_f32_dpp v109, v93, v93 row_ror:8 row_mask:0xf bank_mask:0x1
	ds_read_b128 v[52:55], v0 offset:30080
	v_pk_fma_f32 v[4:5], v[94:95], v[72:73], v[96:97] op_sel_hi:[0,1,1] neg_lo:[1,0,0] neg_hi:[1,0,0]
	v_pk_fma_f32 v[6:7], v[94:95], v[74:75], v[98:99] op_sel_hi:[0,1,1] neg_lo:[1,0,0] neg_hi:[1,0,0]
	s_waitcnt lgkmcnt(5)
; __device__ __forceinline__ void rwkv_scan2_item(const Params& p, int item, char* ldsraw) {
;     ...
;         R_LOAD(0)
;         float sakA = 0.f, sakB = 0.f;
; #pragma unroll
;         for (int q = 0; q < 16; q++) {
;           const f32x4 cw = nw, ckk = nkk, ckka = nkka, ck = nk; const float cvA = nvA, cvB = nvB;
;           if (q < 15) R_LOAD(q + 1)
;           __builtin_amdgcn_sched_barrier(0);
;           float mA0 = mul_s(a0, ckk.x), mA1 = mul_s(a2, ckk.z), mB0 = mul_s(b0, ckk.x), mB1 = mul_s(b2, ckk.z);
;           mA0 = fma_s(a1, ckk.y, mA0); mA1 = fma_s(a3, ckk.w, mA1); mB0 = fma_s(b1, ckk.y, mB0); mB1 = fma_s(b3, ckk.w, mB1);
;           float psA = add_s(mA0, mA1), psB = add_s(mB0, mB1);
;           psA = row16_sum(psA); psB = row16_sum(psB);
;           { const float t0 = fnma_s(psA, ckka.x, mul_s(cvA, ck.x)), t1 = fnma_s(psA, ckka.y, mul_s(cvA, ck.y));
;             const float t2 = fnma_s(psA, ckka.z, mul_s(cvA, ck.z)), t3 = fnma_s(psA, ckka.w, mul_s(cvA, ck.w));
;             a0 = fma_s(a0, cw.x, t0); a1 = fma_s(a1, cw.y, t1); a2 = fma_s(a2, cw.z, t2); a3 = fma_s(a3, cw.w, t3); }
;           { const float t0 = fnma_s(psB, ckka.x, mul_s(cvB, ck.x)), t1 = fnma_s(psB, ckka.y, mul_s(cvB, ck.y));
;             const float t2 = fnma_s(psB, ckka.z, mul_s(cvB, ck.z)), t3 = fnma_s(psB, ckka.w, mul_s(cvB, ck.w));
;             b0 = fma_s(b0, cw.x, t0); b1 = fma_s(b1, cw.y, t1); b2 = fma_s(b2, cw.z, t2); b3 = fma_s(b3, cw.w, t3); }
;           sakA = sel_eq(sakA, psA, jl, q); sakB = sel_eq(sakB, psB, jl, q);
;         }
;     ...
;         SA[(c & 1) * 256 + jl * 16 + row8] = sakA; SA[(c & 1) * 256 + jl * 16 + 8 + row8] = sakB;
;       }
;     } else {
;       if (c >= 1) {
;         const float* d = buf + bprev * CH + jl * 4;
;         const float* dvp = buf + bprev * CH + 320 + row8;
;         const float* dcp = buf + bprev * CH + 336;
;         const float* sap = SA + ((c - 1) & 1) * 256 + row8;
;         f32x4 nw, nkka, nk, nwr; float nvA, nvB, nsA, nsB; f32x2 ncc;
;     ...
;         Y_LOAD(0)
;         float ykA = 0.f, ykB = 0.f;
; #pragma unroll
;         for (int q = 0; q < 16; q++) {
;           const f32x4 cw = nw, ckka = nkka, ck = nk, cwr = nwr; const float cvA = nvA, cvB = nvB, psA = nsA, psB = nsB; const f32x2 ccc = ncc;
;           if (q < 15) Y_LOAD(q + 1)
;           __builtin_amdgcn_sched_barrier(0);
	v_pk_mul_f32 v[88:89], v[4:5], v[142:143] op_sel_hi:[0,1]
	v_pk_mul_f32 v[90:91], v[6:7], v[146:147] op_sel_hi:[0,1]
	v_pk_fma_f32 v[88:89], v[4:5], v[144:145], v[88:89] op_sel:[1,0,0] op_sel_hi:[1,1,1]
	v_pk_fma_f32 v[90:91], v[6:7], v[148:149], v[90:91] op_sel:[1,0,0] op_sel_hi:[1,1,1]
	v_pk_add_f32 v[136:137], v[88:89], v[90:91]
	v_pk_mul_f32 v[96:97], v[84:85], v[154:155] op_sel:[1,0] op_sel_hi:[1,1]
	v_pk_mul_f32 v[98:99], v[84:85], v[156:157] op_sel:[1,0] op_sel_hi:[1,1]
	v_add_f32_dpp v93, v136, v136 quad_perm:[1,0,3,2] row_mask:0xf bank_mask:0xf
	v_pk_fma_f32 v[96:97], v[4:5], v[138:139], v[96:97]
	v_pk_fma_f32 v[98:99], v[6:7], v[140:141], v[98:99]
	v_add_f32_dpp v92, v93, v93 quad_perm:[2,3,0,1] row_mask:0xf bank_mask:0xf
	ds_read_b128 v[64:67], v0 offset:30848
	ds_read_b128 v[68:71], v0 offset:31104
	v_add_f32_dpp v93, v92, v92 row_ror:4 row_mask:0xf bank_mask:0xf
	ds_read_b128 v[76:79], v0 offset:31616
	ds_read_b128 v[60:63], v0 offset:30592
	v_add_f32_dpp v94, v93, v93 row_ror:8 row_mask:0xf bank_mask:0xf
	v_add_f32_dpp v109, v93, v93 row_ror:8 row_mask:0xf bank_mask:0x4
	ds_read_b128 v[72:75], v0 offset:31360
	v_pk_fma_f32 v[4:5], v[94:95], v[150:151], v[96:97] op_sel_hi:[0,1,1] neg_lo:[1,0,0] neg_hi:[1,0,0]
	v_pk_fma_f32 v[6:7], v[94:95], v[152:153], v[98:99] op_sel_hi:[0,1,1] neg_lo:[1,0,0] neg_hi:[1,0,0]
	ds_read_b128 v[80:83], v1 offset:21664
	v_add_f32_dpp v135, v135, v135 row_ror:8 row_mask:0xf bank_mask:0x3
	s_nop 1
	v_add_f32_dpp v135, v137, v137 row_ror:8 row_mask:0xf bank_mask:0xc
	s_waitcnt lgkmcnt(6)
	v_pk_mul_f32 v[88:89], v[4:5], v[44:45] op_sel_hi:[0,1]
	v_pk_mul_f32 v[90:91], v[6:7], v[48:49] op_sel_hi:[0,1]
	v_pk_fma_f32 v[88:89], v[4:5], v[46:47], v[88:89] op_sel:[1,0,0] op_sel_hi:[1,1,1]
	v_pk_fma_f32 v[90:91], v[6:7], v[50:51], v[90:91] op_sel:[1,0,0] op_sel_hi:[1,1,1]
	v_pk_add_f32 v[102:103], v[88:89], v[90:91]
	v_pk_mul_f32 v[96:97], v[86:87], v[56:57] op_sel:[0,0] op_sel_hi:[0,1]
	v_pk_mul_f32 v[98:99], v[86:87], v[58:59] op_sel:[0,0] op_sel_hi:[0,1]
	v_add_f32_dpp v93, v102, v102 quad_perm:[1,0,3,2] row_mask:0xf bank_mask:0xf
	v_pk_fma_f32 v[96:97], v[4:5], v[40:41], v[96:97]
	v_pk_fma_f32 v[98:99], v[6:7], v[42:43], v[98:99]
	v_add_f32_dpp v92, v93, v93 quad_perm:[2,3,0,1] row_mask:0xf bank_mask:0xf
	ds_read_b128 v[142:145], v0 offset:32128
	ds_read_b128 v[146:149], v0 offset:32384
	v_add_f32_dpp v93, v92, v92 row_ror:4 row_mask:0xf bank_mask:0xf
	ds_read_b128 v[154:157], v0 offset:32896
	ds_read_b128 v[138:141], v0 offset:31872
	v_add_f32_dpp v94, v93, v93 row_ror:8 row_mask:0xf bank_mask:0xf
	v_add_f32_dpp v109, v93, v93 row_ror:8 row_mask:0xf bank_mask:0x2
	ds_read_b128 v[150:153], v0 offset:32640
	v_pk_fma_f32 v[4:5], v[94:95], v[52:53], v[96:97] op_sel_hi:[0,1,1] neg_lo:[1,0,0] neg_hi:[1,0,0]
	v_pk_fma_f32 v[6:7], v[94:95], v[54:55], v[98:99] op_sel_hi:[0,1,1] neg_lo:[1,0,0] neg_hi:[1,0,0]
	s_waitcnt lgkmcnt(6)
	v_pk_mul_f32 v[88:89], v[4:5], v[64:65] op_sel_hi:[0,1]
	v_pk_mul_f32 v[90:91], v[6:7], v[68:69] op_sel_hi:[0,1]
	v_pk_fma_f32 v[88:89], v[4:5], v[66:67], v[88:89] op_sel:[1,0,0] op_sel_hi:[1,1,1]
	v_pk_fma_f32 v[90:91], v[6:7], v[70:71], v[90:91] op_sel:[1,0,0] op_sel_hi:[1,1,1]
	v_pk_add_f32 v[132:133], v[88:89], v[90:91]
	v_pk_mul_f32 v[96:97], v[86:87], v[76:77] op_sel:[1,0] op_sel_hi:[1,1]
	v_pk_mul_f32 v[98:99], v[86:87], v[78:79] op_sel:[1,0] op_sel_hi:[1,1]
	v_add_f32_dpp v93, v132, v132 quad_perm:[1,0,3,2] row_mask:0xf bank_mask:0xf
	v_pk_fma_f32 v[96:97], v[4:5], v[60:61], v[96:97]
	v_pk_fma_f32 v[98:99], v[6:7], v[62:63], v[98:99]
	v_add_f32_dpp v92, v93, v93 quad_perm:[2,3,0,1] row_mask:0xf bank_mask:0xf
	ds_read_b128 v[44:47], v0 offset:33408
	ds_read_b128 v[48:51], v0 offset:33664
	v_add_f32_dpp v93, v92, v92 row_ror:4 row_mask:0xf bank_mask:0xf
	ds_read_b128 v[56:59], v0 offset:34176
	ds_read_b128 v[40:43], v0 offset:33152
	v_add_f32_dpp v94, v93, v93 row_ror:8 row_mask:0xf bank_mask:0xf
	v_add_f32_dpp v109, v93, v93 row_ror:8 row_mask:0xf bank_mask:0x8
	ds_read_b128 v[52:55], v0 offset:33920
	v_pk_fma_f32 v[4:5], v[94:95], v[72:73], v[96:97] op_sel_hi:[0,1,1] neg_lo:[1,0,0] neg_hi:[1,0,0]
	v_pk_fma_f32 v[6:7], v[94:95], v[74:75], v[98:99] op_sel_hi:[0,1,1] neg_lo:[1,0,0] neg_hi:[1,0,0]
	v_add_f32_dpp v103, v103, v103 row_ror:8 row_mask:0xf bank_mask:0x3
	s_nop 1
	v_add_f32_dpp v103, v133, v133 row_ror:8 row_mask:0xf bank_mask:0xc
	v_add_f32_dpp v135, v135, v135 row_half_mirror row_mask:0xf bank_mask:0x5
	s_nop 1
	v_add_f32_dpp v135, v103, v103 row_half_mirror row_mask:0xf bank_mask:0xa
	v_cndmask_b32_e64 v106, v135, v101, s[36:37]
	v_cndmask_b32_e64 v107, v101, v135, s[36:37]
	s_nop 1
	v_add_f32_dpp v101, v106, v107 quad_perm:[2,3,0,1] row_mask:0xf bank_mask:0xf
	s_waitcnt lgkmcnt(5)
	v_pk_mul_f32 v[88:89], v[4:5], v[142:143] op_sel_hi:[0,1]
	v_pk_mul_f32 v[90:91], v[6:7], v[146:147] op_sel_hi:[0,1]
	v_pk_fma_f32 v[88:89], v[4:5], v[144:145], v[88:89] op_sel:[1,0,0] op_sel_hi:[1,1,1]
	v_pk_fma_f32 v[90:91], v[6:7], v[148:149], v[90:91] op_sel:[1,0,0] op_sel_hi:[1,1,1]
	v_pk_add_f32 v[104:105], v[88:89], v[90:91]
	v_pk_mul_f32 v[96:97], v[80:81], v[154:155] op_sel:[0,0] op_sel_hi:[0,1]
	v_pk_mul_f32 v[98:99], v[80:81], v[156:157] op_sel:[0,0] op_sel_hi:[0,1]
	v_add_f32_dpp v93, v104, v104 quad_perm:[1,0,3,2] row_mask:0xf bank_mask:0xf
	v_pk_fma_f32 v[96:97], v[4:5], v[138:139], v[96:97]
	v_pk_fma_f32 v[98:99], v[6:7], v[140:141], v[98:99]
	v_add_f32_dpp v92, v93, v93 quad_perm:[2,3,0,1] row_mask:0xf bank_mask:0xf
	ds_read_b128 v[64:67], v0 offset:34688
	ds_read_b128 v[68:71], v0 offset:34944
	v_add_f32_dpp v93, v92, v92 row_ror:4 row_mask:0xf bank_mask:0xf
	ds_read_b128 v[76:79], v0 offset:35456
	ds_read_b128 v[60:63], v0 offset:34432
	v_add_f32_dpp v94, v93, v93 row_ror:8 row_mask:0xf bank_mask:0xf
	v_add_f32_dpp v110, v93, v93 row_ror:8 row_mask:0xf bank_mask:0x1
	ds_read_b128 v[72:75], v0 offset:35200
	v_pk_fma_f32 v[4:5], v[94:95], v[150:151], v[96:97] op_sel_hi:[0,1,1] neg_lo:[1,0,0] neg_hi:[1,0,0]
	v_pk_fma_f32 v[6:7], v[94:95], v[152:153], v[98:99] op_sel_hi:[0,1,1] neg_lo:[1,0,0] neg_hi:[1,0,0]
	s_waitcnt lgkmcnt(5)
; __device__ __forceinline__ void rwkv_scan2_item(const Params& p, int item, char* ldsraw) {
;     ...
;         R_LOAD(0)
;         float sakA = 0.f, sakB = 0.f;
; #pragma unroll
;         for (int q = 0; q < 16; q++) {
;           const f32x4 cw = nw, ckk = nkk, ckka = nkka, ck = nk; const float cvA = nvA, cvB = nvB;
;           if (q < 15) R_LOAD(q + 1)
;           __builtin_amdgcn_sched_barrier(0);
;           float mA0 = mul_s(a0, ckk.x), mA1 = mul_s(a2, ckk.z), mB0 = mul_s(b0, ckk.x), mB1 = mul_s(b2, ckk.z);
;           mA0 = fma_s(a1, ckk.y, mA0); mA1 = fma_s(a3, ckk.w, mA1); mB0 = fma_s(b1, ckk.y, mB0); mB1 = fma_s(b3, ckk.w, mB1);
;           float psA = add_s(mA0, mA1), psB = add_s(mB0, mB1);
;           psA = row16_sum(psA); psB = row16_sum(psB);
;           { const float t0 = fnma_s(psA, ckka.x, mul_s(cvA, ck.x)), t1 = fnma_s(psA, ckka.y, mul_s(cvA, ck.y));
;             const float t2 = fnma_s(psA, ckka.z, mul_s(cvA, ck.z)), t3 = fnma_s(psA, ckka.w, mul_s(cvA, ck.w));
;             a0 = fma_s(a0, cw.x, t0); a1 = fma_s(a1, cw.y, t1); a2 = fma_s(a2, cw.z, t2); a3 = fma_s(a3, cw.w, t3); }
;           { const float t0 = fnma_s(psB, ckka.x, mul_s(cvB, ck.x)), t1 = fnma_s(psB, ckka.y, mul_s(cvB, ck.y));
;             const float t2 = fnma_s(psB, ckka.z, mul_s(cvB, ck.z)), t3 = fnma_s(psB, ckka.w, mul_s(cvB, ck.w));
;             b0 = fma_s(b0, cw.x, t0); b1 = fma_s(b1, cw.y, t1); b2 = fma_s(b2, cw.z, t2); b3 = fma_s(b3, cw.w, t3); }
;           sakA = sel_eq(sakA, psA, jl, q); sakB = sel_eq(sakB, psB, jl, q);
;         }
;     ...
;         SA[(c & 1) * 256 + jl * 16 + row8] = sakA; SA[(c & 1) * 256 + jl * 16 + 8 + row8] = sakB;
;       }
;     } else {
;       if (c >= 1) {
;         const float* d = buf + bprev * CH + jl * 4;
;         const float* dvp = buf + bprev * CH + 320 + row8;
;         const float* dcp = buf + bprev * CH + 336;
;         const float* sap = SA + ((c - 1) & 1) * 256 + row8;
;         f32x4 nw, nkka, nk, nwr; float nvA, nvB, nsA, nsB; f32x2 ncc;
;     ...
;         Y_LOAD(0)
;         float ykA = 0.f, ykB = 0.f;
; #pragma unroll
;         for (int q = 0; q < 16; q++) {
;           const f32x4 cw = nw, ckka = nkka, ck = nk, cwr = nwr; const float cvA = nvA, cvB = nvB, psA = nsA, psB = nsB; const f32x2 ccc = ncc;
;           if (q < 15) Y_LOAD(q + 1)
;           __builtin_amdgcn_sched_barrier(0);
	v_pk_mul_f32 v[88:89], v[4:5], v[44:45] op_sel_hi:[0,1]
	v_pk_mul_f32 v[90:91], v[6:7], v[48:49] op_sel_hi:[0,1]
	v_pk_fma_f32 v[88:89], v[4:5], v[46:47], v[88:89] op_sel:[1,0,0] op_sel_hi:[1,1,1]
	v_pk_fma_f32 v[90:91], v[6:7], v[50:51], v[90:91] op_sel:[1,0,0] op_sel_hi:[1,1,1]
	v_pk_add_f32 v[136:137], v[88:89], v[90:91]
	v_pk_mul_f32 v[96:97], v[80:81], v[56:57] op_sel:[1,0] op_sel_hi:[1,1]
	v_pk_mul_f32 v[98:99], v[80:81], v[58:59] op_sel:[1,0] op_sel_hi:[1,1]
	v_add_f32_dpp v93, v136, v136 quad_perm:[1,0,3,2] row_mask:0xf bank_mask:0xf
	v_pk_fma_f32 v[96:97], v[4:5], v[40:41], v[96:97]
	v_pk_fma_f32 v[98:99], v[6:7], v[42:43], v[98:99]
	v_add_f32_dpp v92, v93, v93 quad_perm:[2,3,0,1] row_mask:0xf bank_mask:0xf
	ds_read_b128 v[142:145], v0 offset:35968
	ds_read_b128 v[146:149], v0 offset:36224
	v_add_f32_dpp v93, v92, v92 row_ror:4 row_mask:0xf bank_mask:0xf
	ds_read_b128 v[154:157], v0 offset:36736
	ds_read_b128 v[138:141], v0 offset:35712
	v_add_f32_dpp v94, v93, v93 row_ror:8 row_mask:0xf bank_mask:0xf
	v_add_f32_dpp v110, v93, v93 row_ror:8 row_mask:0xf bank_mask:0x4
	ds_read_b128 v[150:153], v0 offset:36480
	v_pk_fma_f32 v[4:5], v[94:95], v[52:53], v[96:97] op_sel_hi:[0,1,1] neg_lo:[1,0,0] neg_hi:[1,0,0]
	v_pk_fma_f32 v[6:7], v[94:95], v[54:55], v[98:99] op_sel_hi:[0,1,1] neg_lo:[1,0,0] neg_hi:[1,0,0]
	ds_read_b128 v[84:87], v1 offset:21680
	v_add_f32_dpp v105, v105, v105 row_ror:8 row_mask:0xf bank_mask:0x3
	s_nop 1
	v_add_f32_dpp v105, v137, v137 row_ror:8 row_mask:0xf bank_mask:0xc
	s_waitcnt lgkmcnt(6)
	v_pk_mul_f32 v[88:89], v[4:5], v[64:65] op_sel_hi:[0,1]
	v_pk_mul_f32 v[90:91], v[6:7], v[68:69] op_sel_hi:[0,1]
	v_pk_fma_f32 v[88:89], v[4:5], v[66:67], v[88:89] op_sel:[1,0,0] op_sel_hi:[1,1,1]
	v_pk_fma_f32 v[90:91], v[6:7], v[70:71], v[90:91] op_sel:[1,0,0] op_sel_hi:[1,1,1]
	v_pk_add_f32 v[132:133], v[88:89], v[90:91]
	v_pk_mul_f32 v[96:97], v[82:83], v[76:77] op_sel:[0,0] op_sel_hi:[0,1]
	v_pk_mul_f32 v[98:99], v[82:83], v[78:79] op_sel:[0,0] op_sel_hi:[0,1]
	v_add_f32_dpp v93, v132, v132 quad_perm:[1,0,3,2] row_mask:0xf bank_mask:0xf
	v_pk_fma_f32 v[96:97], v[4:5], v[60:61], v[96:97]
	v_pk_fma_f32 v[98:99], v[6:7], v[62:63], v[98:99]
	v_add_f32_dpp v92, v93, v93 quad_perm:[2,3,0,1] row_mask:0xf bank_mask:0xf
	ds_read_b128 v[44:47], v0 offset:37248
	ds_read_b128 v[48:51], v0 offset:37504
	v_add_f32_dpp v93, v92, v92 row_ror:4 row_mask:0xf bank_mask:0xf
	ds_read_b128 v[56:59], v0 offset:38016
	ds_read_b128 v[40:43], v0 offset:36992
	v_add_f32_dpp v94, v93, v93 row_ror:8 row_mask:0xf bank_mask:0xf
	v_add_f32_dpp v110, v93, v93 row_ror:8 row_mask:0xf bank_mask:0x2
	ds_read_b128 v[52:55], v0 offset:37760
	v_pk_fma_f32 v[4:5], v[94:95], v[72:73], v[96:97] op_sel_hi:[0,1,1] neg_lo:[1,0,0] neg_hi:[1,0,0]
	v_pk_fma_f32 v[6:7], v[94:95], v[74:75], v[98:99] op_sel_hi:[0,1,1] neg_lo:[1,0,0] neg_hi:[1,0,0]
	s_waitcnt lgkmcnt(6)
	v_pk_mul_f32 v[88:89], v[4:5], v[142:143] op_sel_hi:[0,1]
	v_pk_mul_f32 v[90:91], v[6:7], v[146:147] op_sel_hi:[0,1]
	v_pk_fma_f32 v[88:89], v[4:5], v[144:145], v[88:89] op_sel:[1,0,0] op_sel_hi:[1,1,1]
	v_pk_fma_f32 v[90:91], v[6:7], v[148:149], v[90:91] op_sel:[1,0,0] op_sel_hi:[1,1,1]
	v_pk_add_f32 v[102:103], v[88:89], v[90:91]
	v_pk_mul_f32 v[96:97], v[82:83], v[154:155] op_sel:[1,0] op_sel_hi:[1,1]
	v_pk_mul_f32 v[98:99], v[82:83], v[156:157] op_sel:[1,0] op_sel_hi:[1,1]
	v_add_f32_dpp v93, v102, v102 quad_perm:[1,0,3,2] row_mask:0xf bank_mask:0xf
	v_pk_fma_f32 v[96:97], v[4:5], v[138:139], v[96:97]
	v_pk_fma_f32 v[98:99], v[6:7], v[140:141], v[98:99]
	v_add_f32_dpp v92, v93, v93 quad_perm:[2,3,0,1] row_mask:0xf bank_mask:0xf
	ds_read_b128 v[64:67], v0 offset:38528
	ds_read_b128 v[68:71], v0 offset:38784
	v_add_f32_dpp v93, v92, v92 row_ror:4 row_mask:0xf bank_mask:0xf
	ds_read_b128 v[76:79], v0 offset:39296
	ds_read_b128 v[60:63], v0 offset:38272
	v_add_f32_dpp v94, v93, v93 row_ror:8 row_mask:0xf bank_mask:0xf
	v_add_f32_dpp v110, v93, v93 row_ror:8 row_mask:0xf bank_mask:0x8
	ds_read_b128 v[72:75], v0 offset:39040
	v_pk_fma_f32 v[4:5], v[94:95], v[150:151], v[96:97] op_sel_hi:[0,1,1] neg_lo:[1,0,0] neg_hi:[1,0,0]
	v_pk_fma_f32 v[6:7], v[94:95], v[152:153], v[98:99] op_sel_hi:[0,1,1] neg_lo:[1,0,0] neg_hi:[1,0,0]
	v_add_f32_dpp v133, v133, v133 row_ror:8 row_mask:0xf bank_mask:0x3
	s_nop 1
	v_add_f32_dpp v133, v103, v103 row_ror:8 row_mask:0xf bank_mask:0xc
	v_add_f32_dpp v105, v105, v105 row_half_mirror row_mask:0xf bank_mask:0x5
	s_nop 1
	v_add_f32_dpp v105, v133, v133 row_half_mirror row_mask:0xf bank_mask:0xa
	s_waitcnt lgkmcnt(5)
	v_pk_mul_f32 v[88:89], v[4:5], v[44:45] op_sel_hi:[0,1]
	v_pk_mul_f32 v[90:91], v[6:7], v[48:49] op_sel_hi:[0,1]
	v_pk_fma_f32 v[88:89], v[4:5], v[46:47], v[88:89] op_sel:[1,0,0] op_sel_hi:[1,1,1]
	v_pk_fma_f32 v[90:91], v[6:7], v[50:51], v[90:91] op_sel:[1,0,0] op_sel_hi:[1,1,1]
	v_pk_add_f32 v[134:135], v[88:89], v[90:91]
	v_pk_mul_f32 v[96:97], v[84:85], v[56:57] op_sel:[0,0] op_sel_hi:[0,1]
	v_pk_mul_f32 v[98:99], v[84:85], v[58:59] op_sel:[0,0] op_sel_hi:[0,1]
	v_add_f32_dpp v93, v134, v134 quad_perm:[1,0,3,2] row_mask:0xf bank_mask:0xf
	v_pk_fma_f32 v[96:97], v[4:5], v[40:41], v[96:97]
	v_pk_fma_f32 v[98:99], v[6:7], v[42:43], v[98:99]
	v_add_f32_dpp v92, v93, v93 quad_perm:[2,3,0,1] row_mask:0xf bank_mask:0xf
	ds_read_b128 v[142:145], v0 offset:39808
	ds_read_b128 v[146:149], v0 offset:40064
	v_add_f32_dpp v93, v92, v92 row_ror:4 row_mask:0xf bank_mask:0xf
	ds_read_b128 v[154:157], v0 offset:40576
	ds_read_b128 v[138:141], v0 offset:39552
	v_add_f32_dpp v94, v93, v93 row_ror:8 row_mask:0xf bank_mask:0xf
	v_add_f32_dpp v111, v93, v93 row_ror:8 row_mask:0xf bank_mask:0x1
	ds_read_b128 v[150:153], v0 offset:40320
	v_pk_fma_f32 v[4:5], v[94:95], v[52:53], v[96:97] op_sel_hi:[0,1,1] neg_lo:[1,0,0] neg_hi:[1,0,0]
	v_pk_fma_f32 v[6:7], v[94:95], v[54:55], v[98:99] op_sel_hi:[0,1,1] neg_lo:[1,0,0] neg_hi:[1,0,0]
	s_waitcnt lgkmcnt(5)
; __device__ __forceinline__ float bf2f(unsigned short b) { return __uint_as_float(((unsigned)b) << 16); }
; __device__ __forceinline__ unsigned short f2bf(float f) { unsigned r; asm("v_cvt_pk_bf16_f32 %0, %1, %1" : "=v"(r) : "v"(f)); return (unsigned short)(r & 0xffffu); }
; __device__ __forceinline__ float bflo(unsigned u) { return __uint_as_float(u << 16); }
; __device__ __forceinline__ float bfhi(unsigned u) { return __uint_as_float(u & 0xffff0000u); }
; template <int VAR>
; __device__ __forceinline__ void rwkv_scan_item(const Params& p, int item, char* ldsraw) {
;     ...
;   auto store = [&](int bi) {
;     float* d = buf + bi * 16 * STEP + st * STEP;
;     *(f32x4*)(d + part * 4) = pw;
;     *(f32x4*)(d + 64 + part * 4) = (f32x4){bflo(pkk[0]), bfhi(pkk[0]), bflo(pkk[1]), bfhi(pkk[1])};
;     *(f32x4*)(d + 128 + part * 4) = (f32x4){bflo(pkka[0]), bfhi(pkka[0]), bflo(pkka[1]), bfhi(pkka[1])};
;     *(f32x4*)(d + 192 + part * 4) = (f32x4){bflo(pk[0]), bfhi(pk[0]), bflo(pk[1]), bfhi(pk[1])};
;     *(f32x4*)(d + 256 + part * 4) = (f32x4){bflo(pwr[0]), bfhi(pwr[0]), bflo(pwr[1]), bfhi(pwr[1])};
;     d[320 + part] = bf2f(pv);
;     if (part < 2) d[336 + part] = pc;
;   };
;     ...
;     for (int q = 0; q < (VAR == 4 ? 0 : 16); q++) {
;       const f32x4 cw = nw, ckk = nkk, ckka = nkka, ck = nk, cwr = nwr; const float cv = nv; const f32x2 ccc = ncc;
;       if (q < 15 && VAR != 3) SCAN_LOAD(q + 1)
;       __builtin_amdgcn_sched_barrier(0);
;       float m0 = mul_s(s0, ckk.x), m1 = mul_s(s2, ckk.z), n0 = mul_s(s0, cwr.x), n1 = mul_s(s2, cwr.z);
;       m0 = fma_s(s1, ckk.y, m0); m1 = fma_s(s3, ckk.w, m1); n0 = fma_s(s1, cwr.y, n0); n1 = fma_s(s3, cwr.w, n1);
;       float psa = add_s(m0, m1), pu = add_s(n0, n1);
;       if (VAR != 2) { psa = row16_sum(psa); pu = row16_sum(pu); }
;       const float t0 = fnma_s(psa, ckka.x, mul_s(cv, ck.x)), t1 = fnma_s(psa, ckka.y, mul_s(cv, ck.y));
;       const float t2 = fnma_s(psa, ckka.z, mul_s(cv, ck.z)), t3 = fnma_s(psa, ckka.w, mul_s(cv, ck.w));
;       s0 = fma_s(s0, cw.x, t0); s1 = fma_s(s1, cw.y, t1); s2 = fma_s(s2, cw.z, t2); s3 = fma_s(s3, cw.w, t3);
;       const float y = fnma_s(psa, ccc.x, fma_s(cv, ccc.y, pu));
;       ykeep = sel_eq(ykeep, y, jl, q);
;     }
;     if (c + 1 < 256) store((c + 1) & 1);
;     __builtin_amdgcn_sched_barrier(0);
;     yout[(size_t)c * 16 * 1024] = f2bf(ykeep);
;     __syncthreads();
;   }
	v_pk_mul_f32 v[88:89], v[4:5], v[64:65] op_sel_hi:[0,1]
	v_pk_mul_f32 v[90:91], v[6:7], v[68:69] op_sel_hi:[0,1]
	v_pk_fma_f32 v[88:89], v[4:5], v[66:67], v[88:89] op_sel:[1,0,0] op_sel_hi:[1,1,1]
	v_pk_fma_f32 v[90:91], v[6:7], v[70:71], v[90:91] op_sel:[1,0,0] op_sel_hi:[1,1,1]
	v_pk_add_f32 v[136:137], v[88:89], v[90:91]
	v_pk_mul_f32 v[96:97], v[84:85], v[76:77] op_sel:[1,0] op_sel_hi:[1,1]
	v_pk_mul_f32 v[98:99], v[84:85], v[78:79] op_sel:[1,0] op_sel_hi:[1,1]
	v_add_f32_dpp v93, v136, v136 quad_perm:[1,0,3,2] row_mask:0xf bank_mask:0xf
	v_pk_fma_f32 v[96:97], v[4:5], v[60:61], v[96:97]
	v_pk_fma_f32 v[98:99], v[6:7], v[62:63], v[98:99]
	v_add_f32_dpp v92, v93, v93 quad_perm:[2,3,0,1] row_mask:0xf bank_mask:0xf
	ds_read_b128 v[44:47], v0 offset:41088
	ds_read_b128 v[48:51], v0 offset:41344
	v_add_f32_dpp v93, v92, v92 row_ror:4 row_mask:0xf bank_mask:0xf
	ds_read_b128 v[56:59], v0 offset:41856
	ds_read_b128 v[40:43], v0 offset:40832
	v_add_f32_dpp v94, v93, v93 row_ror:8 row_mask:0xf bank_mask:0xf
	v_add_f32_dpp v111, v93, v93 row_ror:8 row_mask:0xf bank_mask:0x4
	ds_read_b128 v[52:55], v0 offset:41600
	v_pk_fma_f32 v[4:5], v[94:95], v[72:73], v[96:97] op_sel_hi:[0,1,1] neg_lo:[1,0,0] neg_hi:[1,0,0]
	v_pk_fma_f32 v[6:7], v[94:95], v[74:75], v[98:99] op_sel_hi:[0,1,1] neg_lo:[1,0,0] neg_hi:[1,0,0]
	ds_read_b32 v112, v10 offset:21632
	ds_read_b64 v[114:115], v11 offset:21632
	v_add_f32_dpp v135, v135, v135 row_ror:8 row_mask:0xf bank_mask:0x3
	s_nop 1
	v_add_f32_dpp v135, v137, v137 row_ror:8 row_mask:0xf bank_mask:0xc
	s_waitcnt lgkmcnt(7)
	v_pk_mul_f32 v[88:89], v[4:5], v[142:143] op_sel_hi:[0,1]
	v_pk_mul_f32 v[90:91], v[6:7], v[146:147] op_sel_hi:[0,1]
	v_pk_fma_f32 v[88:89], v[4:5], v[144:145], v[88:89] op_sel:[1,0,0] op_sel_hi:[1,1,1]
	v_pk_fma_f32 v[90:91], v[6:7], v[148:149], v[90:91] op_sel:[1,0,0] op_sel_hi:[1,1,1]
	v_pk_add_f32 v[102:103], v[88:89], v[90:91]
	v_pk_mul_f32 v[96:97], v[86:87], v[154:155] op_sel:[0,0] op_sel_hi:[0,1]
	v_pk_mul_f32 v[98:99], v[86:87], v[156:157] op_sel:[0,0] op_sel_hi:[0,1]
	v_add_f32_dpp v93, v102, v102 quad_perm:[1,0,3,2] row_mask:0xf bank_mask:0xf
	v_pk_fma_f32 v[96:97], v[4:5], v[138:139], v[96:97]
	v_pk_fma_f32 v[98:99], v[6:7], v[140:141], v[98:99]
	v_add_f32_dpp v92, v93, v93 quad_perm:[2,3,0,1] row_mask:0xf bank_mask:0xf
	s_nop 1
	v_add_f32_dpp v93, v92, v92 row_ror:4 row_mask:0xf bank_mask:0xf
	s_nop 1
	v_add_f32_dpp v94, v93, v93 row_ror:8 row_mask:0xf bank_mask:0xf
	v_add_f32_dpp v111, v93, v93 row_ror:8 row_mask:0xf bank_mask:0x2
	v_pk_fma_f32 v[4:5], v[94:95], v[150:151], v[96:97] op_sel_hi:[0,1,1] neg_lo:[1,0,0] neg_hi:[1,0,0]
	v_pk_fma_f32 v[6:7], v[94:95], v[152:153], v[98:99] op_sel_hi:[0,1,1] neg_lo:[1,0,0] neg_hi:[1,0,0]
	s_waitcnt lgkmcnt(2)
	v_pk_mul_f32 v[88:89], v[4:5], v[44:45] op_sel_hi:[0,1]
	v_pk_mul_f32 v[90:91], v[6:7], v[48:49] op_sel_hi:[0,1]
	v_pk_fma_f32 v[88:89], v[4:5], v[46:47], v[88:89] op_sel:[1,0,0] op_sel_hi:[1,1,1]
	v_pk_fma_f32 v[90:91], v[6:7], v[50:51], v[90:91] op_sel:[1,0,0] op_sel_hi:[1,1,1]
	v_pk_add_f32 v[132:133], v[88:89], v[90:91]
	v_pk_mul_f32 v[96:97], v[86:87], v[56:57] op_sel:[1,0] op_sel_hi:[1,1]
	v_pk_mul_f32 v[98:99], v[86:87], v[58:59] op_sel:[1,0] op_sel_hi:[1,1]
	v_add_f32_dpp v93, v132, v132 quad_perm:[1,0,3,2] row_mask:0xf bank_mask:0xf
	v_pk_fma_f32 v[96:97], v[4:5], v[40:41], v[96:97]
	v_pk_fma_f32 v[98:99], v[6:7], v[42:43], v[98:99]
	v_add_f32_dpp v92, v93, v93 quad_perm:[2,3,0,1] row_mask:0xf bank_mask:0xf
	s_nop 1
	v_add_f32_dpp v93, v92, v92 row_ror:4 row_mask:0xf bank_mask:0xf
	s_nop 1
	v_add_f32_dpp v94, v93, v93 row_ror:8 row_mask:0xf bank_mask:0xf
	v_add_f32_dpp v111, v93, v93 row_ror:8 row_mask:0xf bank_mask:0x8
	v_pk_fma_f32 v[4:5], v[94:95], v[52:53], v[96:97] op_sel_hi:[0,1,1] neg_lo:[1,0,0] neg_hi:[1,0,0]
	v_pk_fma_f32 v[6:7], v[94:95], v[54:55], v[98:99] op_sel_hi:[0,1,1] neg_lo:[1,0,0] neg_hi:[1,0,0]
	v_add_f32_dpp v103, v103, v103 row_ror:8 row_mask:0xf bank_mask:0x3
	s_nop 1
	v_add_f32_dpp v103, v133, v133 row_ror:8 row_mask:0xf bank_mask:0xc
	v_add_f32_dpp v135, v135, v135 row_half_mirror row_mask:0xf bank_mask:0x5
	s_nop 1
	v_add_f32_dpp v135, v103, v103 row_half_mirror row_mask:0xf bank_mask:0xa
	v_cndmask_b32_e64 v106, v135, v105, s[36:37]
	v_cndmask_b32_e64 v107, v105, v135, s[36:37]
	s_nop 1
	v_add_f32_dpp v105, v106, v107 quad_perm:[2,3,0,1] row_mask:0xf bank_mask:0xf
	v_cndmask_b32_e64 v106, v105, v101, s[34:35]
	v_cndmask_b32_e64 v107, v101, v105, s[34:35]
	s_nop 1
	v_add_f32_dpp v101, v106, v107 quad_perm:[1,0,3,2] row_mask:0xf bank_mask:0xf
	v_cndmask_b32_e64 v106, v108, v110, s[34:35]
	v_cndmask_b32_e64 v107, v109, v111, s[34:35]
	v_cndmask_b32_e64 v106, v106, v107, s[36:37]
	s_waitcnt lgkmcnt(0)
	v_fma_f32 v101, v112, v115, v101
	v_fma_f32 v101, -v106, v114, v101
	v_cvt_pk_bf16_f32 v107, v101, v101
	global_store_short v16, v107, s[30:31]
	s_cmp_eq_u32 s38, 63
	s_cbranch_scc1 .Lsc_o_nost
	s_waitcnt vmcnt(1)
	ds_write_b128 v2, v[20:23] offset:0
	v_lshlrev_b32_e32 v36, 16, v24
	v_lshlrev_b32_e32 v37, 16, v30
	v_and_b32_e32 v38, 0xffff0000, v24
	v_and_b32_e32 v39, 0xffff0000, v30
	ds_write_b128 v2, v[36:39] offset:256
	v_lshlrev_b32_e32 v40, 16, v25
	v_lshlrev_b32_e32 v41, 16, v31
	v_and_b32_e32 v42, 0xffff0000, v25
	v_and_b32_e32 v43, 0xffff0000, v31
	ds_write_b128 v2, v[40:43] offset:512
	v_lshlrev_b32_e32 v44, 16, v26
	v_and_b32_e32 v45, 0xffff0000, v26
	v_lshlrev_b32_e32 v46, 16, v27
	v_and_b32_e32 v47, 0xffff0000, v27
	ds_write_b128 v2, v[44:47] offset:768
	v_lshlrev_b32_e32 v48, 16, v28
	v_and_b32_e32 v49, 0xffff0000, v28
	v_lshlrev_b32_e32 v50, 16, v29
	v_and_b32_e32 v51, 0xffff0000, v29
	ds_write_b128 v2, v[48:51] offset:1024
	v_lshlrev_b32_e32 v52, 16, v32
	s_cmp_eq_u32 s41, 2
	s_cselect_b32 s2, 0, -1
	v_and_b32_e32 v52, s2, v52
	ds_write_b32 v8, v52 offset:0
	s_mov_b32 s2, 0x00010001
	s_mov_b32 s3, 0x00010001
	s_mov_b64 exec, s[2:3]
	ds_write_b64 v9, v[34:35] offset:0
	s_mov_b64 exec, -1
